# v18 + SwiGLU epilogue row statistics loaded one tile ahead (no vmcnt(0) drain at epilogue start)
# baseline (speedup 1.0000x reference)
; #define SBAR() __builtin_amdgcn_sched_barrier(0)
; DI int v_st64(int k, int c) { const int kk = (k & ~0xC) | ((k & 4) << 1) | ((k & 8) >> 1); return ((kk >> 3) * 2 + (c >> 5)) * 512 + ((kk & 7) * 32 + (c & 31)) * 2; }
; DI void unit(const bf16* __restrict__ QKV, const int* __restrict__ pos, bf16* __restrict__ OA, float* __restrict__ LSE,
;              int b, int h, int d, int r, int qb, float slope, char* lds) {
;     ...
;   char* K_lds = lds + OFF_K; char* V_lds = lds + OFF_V; int* posk = (int*)(lds + OFF_POS); float* ws = (float*)(lds + OFF_WS) + wid * 64;
;   const bf16* base = QKV + (size_t)(b * 8 + h) * SEQ * 64;
;   constexpr size_t PLANE = (size_t)NB * 8 * SEQ * 64 * 2;
;   auto stage = [&](const int i0) {
;     bf16x8 kreg[3], vreg[3];
; #pragma unroll
;     for (int i = 0; i < 3; ++i) { const int idx = tid + (i0 + i) * 512, row = idx >> 3, ch = idx & 7, v = u0 - 64 + row; const bool ok = (v >= 0) && (v < L);
;       const unsigned go = (unsigned)((r + d * (ok ? v : 0)) * 64 + ch * 8) * 2u;
;       kreg[i] = *(const bf16x8*)((const char*)base + PLANE + go); vreg[i] = *(const bf16x8*)((const char*)base + 2 * PLANE + go);
;       if (!ok) { kreg[i] = bf16x8{}; vreg[i] = bf16x8{}; } }
; #pragma unroll
;     for (int i = 0; i < 3; ++i) { const int idx = tid + (i0 + i) * 512, row = idx >> 3, ch = idx & 7;
;       *(bf16x8*)(K_lds + PSWZ(row, ch * 16)) = kreg[i]; *(bf16x8*)(V_lds + v_st64(row, ch * 8)) = vreg[i]; }
;   };
;   stage(0); SBAR(); stage(3); SBAR();
;   float pkv = 3.0e8f; if (tid < 384) { const int v = u0 - 64 + tid; if (v >= 0 && v < L) pkv = (float)pos[b * SEQ + r + d * v]; }
;   const int uq = u0 + wid * 32 + r32, tq = r + d * uq;
;   bf16x8 qr[4];
; #pragma unroll
;   for (int d0 = 0; d0 < 4; ++d0) qr[d0] = *(const bf16x8*)((const char*)base + (unsigned)(tq * 64 + d0 * 16 + hi * 8) * 2u);
;   const int pq = pos[b * SEQ + tq];
;   if (tid < 384) ((float*)posk)[tid] = pkv;
;   __syncthreads();
.LBB0_864:
	s_and_b32 s48, s47, 7
	s_bfe_u32 s30, s47, 0x30007
	s_ff1_i32_b32 s3, s8
	s_lshr_b32 s49, 0x1000, s3
	s_mov_b32 s77, s3
	s_lshl_b32 s31, s2, 8
	s_lshl_b32 s2, s48, 19
	s_lshl_b32 s3, s30, 22
	s_or_b32 s2, s3, s2
	s_add_u32 s16, s10, s2
	v_mov_b32_e32 v4, v242
	s_addc_u32 s17, s11, 0
	s_sub_i32 s50, s31, 64
	s_add_u32 s18, s16, 0x2000000
	s_addc_u32 s19, s17, 0
	s_add_u32 s20, s16, 0x4000000
	s_addc_u32 s21, s17, 0
	s_lshl_b32 s94, s30, 12
	s_or_b32 s94, s15, s94
	v_ashrrev_i32_e32 v6, 6, v4
	v_lshlrev_b32_e32 v102, 5, v6
	v_and_b32_e32 v100, 31, v4
	v_add_u32_e32 v0, s31, v102
	v_or_b32_e32 v0, v0, v100
	v_bfe_u32 v101, v4, 5, 1
	v_lshlrev_b32_e32 v0, s77, v0
	v_add_u32_e32 v7, s15, v0
	v_lshlrev_b32_e32 v92, 4, v101
	v_lshl_or_b32 v8, v7, 7, v92
	v_lshl_add_u32 v94, s30, 12, v7
	global_load_dwordx4 v[0:3], v8, s[16:17]
	global_load_dwordx4 v[88:91], v8, s[16:17] offset:32
	global_load_dwordx4 v[84:87], v8, s[16:17] offset:64
	global_load_dwordx4 v[80:83], v8, s[16:17] offset:96
	v_ashrrev_i32_e32 v95, 31, v94
	v_lshl_add_u64 v[8:9], v[94:95], 2, s[40:41]
	global_load_dword v103, v[8:9], off
	v_add_u32_e32 v214, s50, v234
	s_add_i32 s95, s50, 64
	v_add_u32_e32 v215, s95, v234
	s_add_i32 s95, s50, 128
	v_add_u32_e32 v216, s95, v234
	s_add_i32 s95, s50, 192
	v_add_u32_e32 v217, s95, v234
	s_add_i32 s95, s50, 256
	v_add_u32_e32 v218, s95, v234
	s_add_i32 s95, s50, 320
	v_add_u32_e32 v219, s95, v234
	v_add_u32_e32 v220, s50, v4
	v_cmp_gt_u32_e64 s[80:81], s49, v214
	v_cmp_gt_u32_e64 s[82:83], s49, v215
	v_cmp_gt_u32_e64 s[84:85], s49, v216
	v_cmp_gt_u32_e64 s[86:87], s49, v217
	v_cmp_gt_u32_e64 s[88:89], s49, v218
	v_cmp_gt_u32_e64 s[90:91], s49, v219
	v_cmp_gt_u32_e64 s[92:93], s49, v220
	v_cmp_gt_i32_e32 vcc, s42, v4
	v_cndmask_b32_e64 v214, 0, v214, s[80:81]
	v_cndmask_b32_e64 v215, 0, v215, s[82:83]
	v_cndmask_b32_e64 v216, 0, v216, s[84:85]
	v_cndmask_b32_e64 v217, 0, v217, s[86:87]
	v_cndmask_b32_e64 v218, 0, v218, s[88:89]
	v_cndmask_b32_e64 v219, 0, v219, s[90:91]
	s_and_b64 s[92:93], s[92:93], vcc
	v_lshlrev_b32_e32 v214, s77, v214
	v_lshlrev_b32_e32 v215, s77, v215
	v_lshlrev_b32_e32 v216, s77, v216
	v_lshlrev_b32_e32 v217, s77, v217
	v_lshlrev_b32_e32 v218, s77, v218
	v_lshlrev_b32_e32 v219, s77, v219
	v_cndmask_b32_e64 v220, 0, v220, s[92:93]
	v_add_u32_e32 v214, s15, v214
	v_add_u32_e32 v215, s15, v215
	v_add_u32_e32 v216, s15, v216
	v_add_u32_e32 v217, s15, v217
	v_add_u32_e32 v218, s15, v218
	v_add_u32_e32 v219, s15, v219
	v_lshlrev_b32_e32 v220, s77, v220
	v_lshl_or_b32 v214, v214, 7, v235
	v_lshl_or_b32 v215, v215, 7, v235
	v_lshl_or_b32 v216, v216, 7, v235
	v_lshl_or_b32 v217, v217, 7, v235
	v_lshl_or_b32 v218, v218, 7, v235
	v_lshl_or_b32 v219, v219, 7, v235
	v_add_lshl_u32 v220, v220, s94, 2
	global_load_dwordx4 v[164:167], v214, s[18:19]
	global_load_dwordx4 v[168:171], v214, s[20:21]
	global_load_dwordx4 v[172:175], v215, s[18:19]
	global_load_dwordx4 v[176:179], v215, s[20:21]
	global_load_dwordx4 v[180:183], v216, s[18:19]
	global_load_dwordx4 v[184:187], v216, s[20:21]
	global_load_dwordx4 v[188:191], v217, s[18:19]
	global_load_dwordx4 v[192:195], v217, s[20:21]
	global_load_dwordx4 v[196:199], v218, s[18:19]
	global_load_dwordx4 v[200:203], v218, s[20:21]
	global_load_dwordx4 v[204:207], v219, s[18:19]
	global_load_dwordx4 v[208:211], v219, s[20:21]
	global_load_dword v213, v220, s[40:41]
	s_waitcnt vmcnt(11)
	ds_write_b128 v222, v[164:167]
	ds_write_b128 v223, v[168:171]
	s_waitcnt vmcnt(9)
	ds_write_b128 v222, v[172:175] offset:8192
	ds_write_b128 v223, v[176:179] offset:8192
	s_waitcnt vmcnt(7)
	ds_write_b128 v222, v[180:183] offset:16384
	ds_write_b128 v223, v[184:187] offset:16384
	s_waitcnt vmcnt(5)
	ds_write_b128 v222, v[188:191] offset:24576
	ds_write_b128 v223, v[192:195] offset:24576
	s_waitcnt vmcnt(3)
	ds_write_b128 v222, v[196:199] offset:32768
	ds_write_b128 v223, v[200:203] offset:32768
	s_waitcnt vmcnt(1)
	ds_write_b128 v222, v[204:207] offset:40960
	ds_write_b128 v223, v[208:211] offset:40960
	s_waitcnt vmcnt(0)
	v_cmp_gt_i32_e32 vcc, s42, v4
	v_cvt_f32_i32_e32 v213, v213
	v_mov_b32_e32 v5, 0x4d8f0d18
	v_cndmask_b32_e64 v5, v5, v213, s[92:93]
	s_and_saveexec_b64 s[2:3], vcc
	v_lshl_add_u32 v7, v4, 2, 0
	v_add_u32_e32 v7, 0x18000, v7
	ds_write_b32 v7, v5
	s_or_b64 exec, exec, s[2:3]
	v_lshlrev_b32_e32 v5, 3, v4
	v_lshlrev_b32_e32 v99, 12, v6
	v_bitop3_b32 v7, v92, v5, s39 bitop3:0x78
	v_lshl_or_b32 v14, v100, 7, v99
	v_add3_u32 v15, 0, v7, v14
	s_waitcnt lgkmcnt(0)
	s_barrier
; #define SBAR() __builtin_amdgcn_sched_barrier(0)
; DI void unit(const bf16* __restrict__ QKV, const int* __restrict__ pos, bf16* __restrict__ OA, float* __restrict__ LSE,
;              int b, int h, int d, int r, int qb, float slope, char* lds) {
;     ...
;   f32x16 p[5];
; #pragma unroll
;   for (int ta = 0; ta < 5; ++ta) { p[ta] = f32x16{};
; #pragma unroll
;     for (int d0 = 0; d0 < 4; ++d0) { const bf16x8 a = *(const bf16x8*)(K_lds + PSWZ(wid * 32 + ta * 32 + r32, (d0 * 16 + hi * 8) * 2));
;       p[ta] = __builtin_amdgcn_mfma_f32_32x32x16_bf16(a, qr[d0], p[ta], 0, 0, 0); }
;     SBAR(); }
;   const float C = 0.125f * 1.4426950408889634f, sl2 = slope * 1.4426950408889634f;
;   const float* pbase = (const float*)posk + wid * 32 + 4 * hi; const float pqf = (float)pq;
;   float mx = -1e30f;
; #pragma unroll
;   for (int ta = 0; ta < 5; ++ta) {
; #pragma unroll
;     for (int g = 0; g < 4; ++g) { const f32x4 pk4 = *(const f32x4*)(pbase + ta * 32 + 8 * g);
; #pragma unroll
;       for (int j = 0; j < 4; ++j) { const int rr = 4 * g + j, kr = j + 8 * g + 4 * hi;
;         float sc = fmaf(__builtin_fabsf(pqf - pk4[j]), -sl2, p[ta][rr] * C);
;         if (ta == 0) sc = (kr >= r32) ? sc : -1e30f;
;         if (ta == 4) sc = (kr <= r32) ? sc : -1e30f;
;         p[ta][rr] = sc; mx = fmaxf(mx, sc); } }
	ds_read_b128 v[6:9], v15
	v_and_b32_e32 v5, 0x70, v5
	v_bitop3_b32 v10, v92, v5, 32 bitop3:0x36
	v_add3_u32 v104, 0, v10, v14
	ds_read_b128 v[10:13], v104
	s_waitcnt vmcnt(4) lgkmcnt(1)
	v_mfma_f32_32x32x16_bf16 v[64:79], v[6:9], v[0:3], 0
	v_bitop3_b32 v6, v92, v5, 64 bitop3:0x36
	v_add3_u32 v108, 0, v6, v14
	ds_read_b128 v[6:9], v108
	v_bitop3_b32 v5, v92, v5, s44 bitop3:0x36
	v_add3_u32 v109, 0, v5, v14
	s_add_i32 s2, s48, 1
	v_cvt_f32_ubyte0_e32 v16, s2
	s_waitcnt vmcnt(3) lgkmcnt(1)
	v_mfma_f32_32x32x16_bf16 v[64:79], v[10:13], v[88:91], v[64:79]
	ds_read_b128 v[10:13], v109
	v_cmp_lt_f32_e32 vcc, s43, v16
	s_and_b64 s[2:3], vcc, exec
	s_cselect_b32 s2, 0xffffffc0, 0
	v_cndmask_b32_e32 v17, 0, v96, vcc
	v_sub_f32_e32 v5, v17, v16
	v_exp_f32_e32 v5, v5
	s_waitcnt vmcnt(2) lgkmcnt(1)
	v_mfma_f32_32x32x16_bf16 v[64:79], v[6:9], v[84:87], v[64:79]
	s_ashr_i32 s15, s14, 31
	v_and_b32_e32 v98, 63, v4
	v_ldexp_f32 v110, v5, s2
	s_waitcnt vmcnt(1) lgkmcnt(0)
	v_mfma_f32_32x32x16_bf16 v[64:79], v[10:13], v[80:83], v[64:79]
	ds_read_b128 v[4:7], v15 offset:4096
	ds_read_b128 v[8:11], v104 offset:4096
	s_waitcnt lgkmcnt(1)
	v_mfma_f32_32x32x16_bf16 v[48:63], v[4:7], v[0:3], 0
	s_waitcnt lgkmcnt(0)
	v_mfma_f32_32x32x16_bf16 v[48:63], v[8:11], v[88:91], v[48:63]
	ds_read_b128 v[4:7], v108 offset:4096
	ds_read_b128 v[8:11], v109 offset:4096
	s_waitcnt lgkmcnt(1)
	v_mfma_f32_32x32x16_bf16 v[48:63], v[4:7], v[84:87], v[48:63]
	s_waitcnt lgkmcnt(0)
	v_mfma_f32_32x32x16_bf16 v[48:63], v[8:11], v[80:83], v[48:63]
	ds_read_b128 v[4:7], v15 offset:8192
	ds_read_b128 v[8:11], v104 offset:8192
	s_waitcnt lgkmcnt(1)
	v_mfma_f32_32x32x16_bf16 v[32:47], v[4:7], v[0:3], 0
	s_waitcnt lgkmcnt(0)
	v_mfma_f32_32x32x16_bf16 v[32:47], v[8:11], v[88:91], v[32:47]
	ds_read_b128 v[4:7], v108 offset:8192
	ds_read_b128 v[8:11], v109 offset:8192
	s_waitcnt lgkmcnt(1)
	v_mfma_f32_32x32x16_bf16 v[32:47], v[4:7], v[84:87], v[32:47]
	s_waitcnt lgkmcnt(0)
	v_mfma_f32_32x32x16_bf16 v[32:47], v[8:11], v[80:83], v[32:47]
	ds_read_b128 v[4:7], v15 offset:12288
	ds_read_b128 v[8:11], v104 offset:12288
	s_waitcnt lgkmcnt(1)
	v_mfma_f32_32x32x16_bf16 v[16:31], v[4:7], v[0:3], 0
	s_waitcnt lgkmcnt(0)
	v_mfma_f32_32x32x16_bf16 v[16:31], v[8:11], v[88:91], v[16:31]
	ds_read_b128 v[4:7], v108 offset:12288
	ds_read_b128 v[8:11], v109 offset:12288
	s_waitcnt lgkmcnt(1)
	v_mfma_f32_32x32x16_bf16 v[16:31], v[4:7], v[84:87], v[16:31]
	s_waitcnt lgkmcnt(0)
	v_mfma_f32_32x32x16_bf16 v[16:31], v[8:11], v[80:83], v[16:31]
	ds_read_b128 v[4:7], v15 offset:16384
	ds_read_b128 v[104:107], v104 offset:16384
	s_waitcnt lgkmcnt(1)
	v_mfma_f32_32x32x16_bf16 v[0:15], v[4:7], v[0:3], 0
	s_waitcnt lgkmcnt(0)
	v_mfma_f32_32x32x16_bf16 v[0:15], v[104:107], v[88:91], v[0:15]
	ds_read_b128 v[88:91], v108 offset:16384
	ds_read_b128 v[104:107], v109 offset:16384
	s_waitcnt lgkmcnt(1)
	v_mfma_f32_32x32x16_bf16 v[0:15], v[88:91], v[84:87], v[0:15]
	s_waitcnt lgkmcnt(0)
	v_mfma_f32_32x32x16_bf16 v[0:15], v[104:107], v[80:83], v[0:15]
	v_lshlrev_b32_e32 v80, 2, v102
	v_add3_u32 v88, s46, v80, v92
	ds_read_b128 v[80:83], v88
	ds_read_b128 v[84:87], v88 offset:32
	s_waitcnt vmcnt(0)
	v_cvt_f32_i32_e32 v89, v103
	v_lshlrev_b32_e32 v90, 2, v101
	v_mul_f32_e32 v91, 0xbfb8aa3b, v110
	v_fma_f32 v64, v64, s76, v134
	s_waitcnt lgkmcnt(1)
	v_sub_f32_e32 v80, v89, v80
	v_fma_f32 v80, |v80|, v91, v64
	v_sub_f32_e32 v81, v89, v81
	v_fma_f32 v65, v65, s76, v135
	v_fma_f32 v81, |v81|, v91, v65
	v_fma_f32 v66, v66, s76, v136
	v_sub_f32_e32 v65, v89, v82
	v_fma_f32 v82, |v65|, v91, v66
	v_fma_f32 v66, v67, s76, v137
	v_sub_f32_e32 v65, v89, v83
	v_fma_f32 v83, |v65|, v91, v66
	v_fma_f32 v66, v68, s76, v138
	s_waitcnt lgkmcnt(0)
	v_sub_f32_e32 v65, v89, v84
	v_fma_f32 v84, |v65|, v91, v66
	v_fma_f32 v66, v69, s76, v139
	v_sub_f32_e32 v65, v89, v85
	v_max3_f32 v64, v80, s45, v81
	v_fma_f32 v85, |v65|, v91, v66
	v_max3_f32 v64, v64, v82, v83
	v_max3_f32 v68, v64, v84, v85
	v_sub_f32_e32 v64, v89, v86
	v_fma_f32 v65, v70, s76, v140
	v_fma_f32 v86, |v64|, v91, v65
	v_fma_f32 v65, v71, s76, v141
	v_sub_f32_e32 v64, v89, v87
	v_fma_f32 v87, |v64|, v91, v65
	ds_read_b128 v[64:67], v88 offset:64
	v_fma_f32 v72, v72, s76, v142
	v_max3_f32 v107, v68, v86, v87
	ds_read_b128 v[68:71], v88 offset:96
	s_waitcnt lgkmcnt(1)
	v_sub_f32_e32 v64, v89, v64
	v_fma_f32 v72, |v64|, v91, v72
	v_sub_f32_e32 v64, v89, v65
	v_fma_f32 v65, v73, s76, v143
	v_fma_f32 v73, |v64|, v91, v65
	v_sub_f32_e32 v65, v89, v66
	v_fma_f32 v66, v74, s76, v144
	v_max3_f32 v64, v107, v72, v73
	v_fma_f32 v74, |v65|, v91, v66
	v_fma_f32 v66, v75, s76, v145
	v_sub_f32_e32 v65, v89, v67
	v_fma_f32 v75, |v65|, v91, v66
	v_fma_f32 v66, v76, s76, v148
	s_waitcnt lgkmcnt(0)
	v_sub_f32_e32 v65, v89, v68
	v_fma_f32 v76, |v65|, v91, v66
	v_fma_f32 v66, v77, s76, v149
	v_sub_f32_e32 v65, v89, v69
	v_fma_f32 v77, |v65|, v91, v66
	v_fma_f32 v66, v78, s76, v150
	v_sub_f32_e32 v65, v89, v70
	v_fma_f32 v78, |v65|, v91, v66
	v_fma_f32 v66, v79, s76, v152
	v_max3_f32 v64, v64, v74, v75
	v_sub_f32_e32 v65, v89, v71
	v_fma_f32 v79, |v65|, v91, v66
	v_max3_f32 v64, v64, v76, v77
	s_nop 0
	v_max3_f32 v115, v64, v78, v79
	ds_read_b128 v[64:67], v88 offset:128
	ds_read_b128 v[68:71], v88 offset:160
	v_mul_f32_e32 v49, s76, v49
	v_mul_f32_e32 v50, s76, v50
	v_mul_f32_e32 v48, s76, v48
	s_waitcnt lgkmcnt(1)
	v_sub_f32_e32 v65, v89, v65
	v_fma_f32 v65, |v65|, v91, v49
	v_sub_f32_e32 v49, v89, v66
	v_sub_f32_e32 v64, v89, v64
	v_fma_f32 v66, |v49|, v91, v50
	v_sub_f32_e32 v49, v89, v67
	v_mul_f32_e32 v50, s76, v51
	v_fma_f32 v64, |v64|, v91, v48
	v_fma_f32 v67, |v49|, v91, v50
	s_waitcnt lgkmcnt(0)
; DI void unit(const bf16* __restrict__ QKV, const int* __restrict__ pos, bf16* __restrict__ OA, float* __restrict__ LSE,
;              int b, int h, int d, int r, int qb, float slope, char* lds) {
;     ...
;   for (int ta = 0; ta < 5; ++ta) {
; #pragma unroll
;     for (int g = 0; g < 4; ++g) { const f32x4 pk4 = *(const f32x4*)(pbase + ta * 32 + 8 * g);
; #pragma unroll
;       for (int j = 0; j < 4; ++j) { const int rr = 4 * g + j, kr = j + 8 * g + 4 * hi;
;         float sc = fmaf(__builtin_fabsf(pqf - pk4[j]), -sl2, p[ta][rr] * C);
;         if (ta == 0) sc = (kr >= r32) ? sc : -1e30f;
;         if (ta == 4) sc = (kr <= r32) ? sc : -1e30f;
;         p[ta][rr] = sc; mx = fmaxf(mx, sc); } }
	v_sub_f32_e32 v49, v89, v68
	v_mul_f32_e32 v50, s76, v52
	v_max3_f32 v48, v115, v64, v65
	v_fma_f32 v68, |v49|, v91, v50
	v_sub_f32_e32 v49, v89, v69
	v_mul_f32_e32 v50, s76, v53
	v_max3_f32 v48, v48, v66, v67
	v_fma_f32 v69, |v49|, v91, v50
	v_max3_f32 v52, v48, v68, v69
	v_sub_f32_e32 v48, v89, v70
	v_mul_f32_e32 v49, s76, v54
	v_fma_f32 v70, |v48|, v91, v49
	ds_read_b128 v[48:51], v88 offset:192
	v_sub_f32_e32 v53, v89, v71
	v_mul_f32_e32 v54, s76, v55
	v_fma_f32 v71, |v53|, v91, v54
	v_max3_f32 v115, v52, v70, v71
	ds_read_b128 v[52:55], v88 offset:224
	s_waitcnt lgkmcnt(1)
	v_sub_f32_e32 v48, v89, v48
	v_mul_f32_e32 v56, s76, v56
	v_fma_f32 v56, |v48|, v91, v56
	v_sub_f32_e32 v48, v89, v49
	v_mul_f32_e32 v49, s76, v57
	v_fma_f32 v57, |v48|, v91, v49
	v_sub_f32_e32 v49, v89, v50
	v_mul_f32_e32 v50, s76, v58
	v_fma_f32 v58, |v49|, v91, v50
	v_sub_f32_e32 v49, v89, v51
	v_mul_f32_e32 v50, s76, v59
	v_fma_f32 v59, |v49|, v91, v50
	s_waitcnt lgkmcnt(0)
	v_sub_f32_e32 v49, v89, v52
	v_mul_f32_e32 v50, s76, v60
	v_fma_f32 v60, |v49|, v91, v50
	v_sub_f32_e32 v49, v89, v53
	v_mul_f32_e32 v50, s76, v61
	v_max3_f32 v48, v115, v56, v57
	v_fma_f32 v61, |v49|, v91, v50
	v_sub_f32_e32 v49, v89, v54
	v_mul_f32_e32 v50, s76, v62
	v_max3_f32 v48, v48, v58, v59
	v_fma_f32 v62, |v49|, v91, v50
	v_sub_f32_e32 v49, v89, v55
	v_mul_f32_e32 v50, s76, v63
	v_max3_f32 v48, v48, v60, v61
	v_fma_f32 v63, |v49|, v91, v50
	v_max3_f32 v115, v48, v62, v63
	ds_read_b128 v[48:51], v88 offset:256
	ds_read_b128 v[52:55], v88 offset:288
	v_mul_f32_e32 v33, s76, v33
	v_mul_f32_e32 v34, s76, v34
	v_mul_f32_e32 v32, s76, v32
	s_waitcnt lgkmcnt(1)
	v_sub_f32_e32 v49, v89, v49
	v_fma_f32 v49, |v49|, v91, v33
	v_sub_f32_e32 v33, v89, v50
	v_sub_f32_e32 v48, v89, v48
	v_fma_f32 v50, |v33|, v91, v34
	v_sub_f32_e32 v33, v89, v51
	v_mul_f32_e32 v34, s76, v35
	v_fma_f32 v48, |v48|, v91, v32
	v_fma_f32 v51, |v33|, v91, v34
	s_waitcnt lgkmcnt(0)
	v_sub_f32_e32 v33, v89, v52
	v_mul_f32_e32 v34, s76, v36
	v_max3_f32 v32, v115, v48, v49
	v_fma_f32 v52, |v33|, v91, v34
	v_sub_f32_e32 v33, v89, v53
	v_mul_f32_e32 v34, s76, v37
	v_max3_f32 v32, v32, v50, v51
	v_fma_f32 v53, |v33|, v91, v34
	v_max3_f32 v36, v32, v52, v53
	v_sub_f32_e32 v32, v89, v54
	v_mul_f32_e32 v33, s76, v38
	v_fma_f32 v54, |v32|, v91, v33
	ds_read_b128 v[32:35], v88 offset:320
	v_sub_f32_e32 v37, v89, v55
	v_mul_f32_e32 v38, s76, v39
	v_fma_f32 v55, |v37|, v91, v38
	v_max3_f32 v115, v36, v54, v55
	ds_read_b128 v[36:39], v88 offset:352
	s_waitcnt lgkmcnt(1)
	v_sub_f32_e32 v32, v89, v32
	v_mul_f32_e32 v40, s76, v40
	v_fma_f32 v40, |v32|, v91, v40
	v_sub_f32_e32 v32, v89, v33
	v_mul_f32_e32 v33, s76, v41
	v_fma_f32 v41, |v32|, v91, v33
	v_sub_f32_e32 v33, v89, v34
	v_mul_f32_e32 v34, s76, v42
	v_fma_f32 v42, |v33|, v91, v34
	v_sub_f32_e32 v33, v89, v35
	v_mul_f32_e32 v34, s76, v43
	v_fma_f32 v43, |v33|, v91, v34
	s_waitcnt lgkmcnt(0)
	v_sub_f32_e32 v33, v89, v36
	v_mul_f32_e32 v34, s76, v44
	v_fma_f32 v44, |v33|, v91, v34
	v_sub_f32_e32 v33, v89, v37
	v_mul_f32_e32 v34, s76, v45
	v_max3_f32 v32, v115, v40, v41
	v_fma_f32 v45, |v33|, v91, v34
	v_sub_f32_e32 v33, v89, v38
	v_mul_f32_e32 v34, s76, v46
	v_max3_f32 v32, v32, v42, v43
	v_fma_f32 v46, |v33|, v91, v34
	v_sub_f32_e32 v33, v89, v39
	v_mul_f32_e32 v34, s76, v47
	v_max3_f32 v32, v32, v44, v45
	v_fma_f32 v47, |v33|, v91, v34
	v_max3_f32 v115, v32, v46, v47
	ds_read_b128 v[32:35], v88 offset:384
	ds_read_b128 v[36:39], v88 offset:416
	v_mul_f32_e32 v17, s76, v17
	v_mul_f32_e32 v18, s76, v18
	v_mul_f32_e32 v16, s76, v16
	s_waitcnt lgkmcnt(1)
	v_sub_f32_e32 v33, v89, v33
	v_fma_f32 v33, |v33|, v91, v17
	v_sub_f32_e32 v17, v89, v34
	v_sub_f32_e32 v32, v89, v32
	v_fma_f32 v34, |v17|, v91, v18
	v_sub_f32_e32 v17, v89, v35
	v_mul_f32_e32 v18, s76, v19
	v_fma_f32 v116, |v32|, v91, v16
	v_fma_f32 v35, |v17|, v91, v18
	s_waitcnt lgkmcnt(0)
	v_sub_f32_e32 v17, v89, v36
	v_mul_f32_e32 v18, s76, v20
	v_max3_f32 v16, v115, v116, v33
	v_fma_f32 v36, |v17|, v91, v18
	v_sub_f32_e32 v17, v89, v37
	v_mul_f32_e32 v18, s76, v21
	v_max3_f32 v16, v16, v34, v35
	v_fma_f32 v37, |v17|, v91, v18
	v_max3_f32 v20, v16, v36, v37
	v_sub_f32_e32 v16, v89, v38
	v_mul_f32_e32 v17, s76, v22
	v_fma_f32 v38, |v16|, v91, v17
	ds_read_b128 v[16:19], v88 offset:448
	v_sub_f32_e32 v21, v89, v39
	v_mul_f32_e32 v22, s76, v23
	v_fma_f32 v39, |v21|, v91, v22
	v_max3_f32 v32, v20, v38, v39
	ds_read_b128 v[20:23], v88 offset:480
	s_waitcnt lgkmcnt(1)
	v_sub_f32_e32 v16, v89, v16
	v_mul_f32_e32 v24, s76, v24
	v_fma_f32 v24, |v16|, v91, v24
	v_sub_f32_e32 v16, v89, v17
	v_mul_f32_e32 v17, s76, v25
	v_fma_f32 v25, |v16|, v91, v17
	v_sub_f32_e32 v17, v89, v18
	v_mul_f32_e32 v18, s76, v26
	v_fma_f32 v26, |v17|, v91, v18
	v_sub_f32_e32 v17, v89, v19
	v_mul_f32_e32 v18, s76, v27
	v_fma_f32 v27, |v17|, v91, v18
	s_waitcnt lgkmcnt(0)
	v_sub_f32_e32 v17, v89, v20
	v_mul_f32_e32 v18, s76, v28
	v_fma_f32 v28, |v17|, v91, v18
	v_sub_f32_e32 v17, v89, v21
	v_mul_f32_e32 v18, s76, v29
	v_max3_f32 v16, v32, v24, v25
	v_fma_f32 v29, |v17|, v91, v18
	v_sub_f32_e32 v17, v89, v22
	v_mul_f32_e32 v18, s76, v30
	v_max3_f32 v16, v16, v26, v27
	v_fma_f32 v30, |v17|, v91, v18
	v_sub_f32_e32 v17, v89, v23
	v_mul_f32_e32 v18, s76, v31
	v_max3_f32 v16, v16, v28, v29
	v_fma_f32 v31, |v17|, v91, v18
	v_max3_f32 v32, v16, v30, v31
	ds_read_b128 v[16:19], v88 offset:512
	ds_read_b128 v[20:23], v88 offset:544
	v_fma_f32 v0, v0, s76, v153
	v_fma_f32 v2, v2, s76, v155
	s_waitcnt lgkmcnt(1)
; #define SBAR() __builtin_amdgcn_sched_barrier(0)
; DI void unit(const bf16* __restrict__ QKV, const int* __restrict__ pos, bf16* __restrict__ OA, float* __restrict__ LSE,
;              int b, int h, int d, int r, int qb, float slope, char* lds) {
;     ...
;   for (int ta = 0; ta < 5; ++ta) {
; #pragma unroll
;     for (int g = 0; g < 4; ++g) { const f32x4 pk4 = *(const f32x4*)(pbase + ta * 32 + 8 * g);
; #pragma unroll
;       for (int j = 0; j < 4; ++j) { const int rr = 4 * g + j, kr = j + 8 * g + 4 * hi;
;         float sc = fmaf(__builtin_fabsf(pqf - pk4[j]), -sl2, p[ta][rr] * C);
;         if (ta == 0) sc = (kr >= r32) ? sc : -1e30f;
;         if (ta == 4) sc = (kr <= r32) ? sc : -1e30f;
;         p[ta][rr] = sc; mx = fmaxf(mx, sc); } }
;     SBAR(); }
;   { auto x = __builtin_amdgcn_permlane32_swap(__float_as_uint(mx), __float_as_uint(mx), false, false); mx = fmaxf(__uint_as_float(x[0]), __uint_as_float(x[1])); }
;   float ls = 0.f;
; #pragma unroll
;   for (int ta = 0; ta < 5; ++ta)
; #pragma unroll
;     for (int rr = 0; rr < 16; ++rr) { p[ta][rr] = __builtin_amdgcn_exp2f(p[ta][rr] - mx); ls += p[ta][rr]; if (rr == 15) SBAR(); }
;   { auto x = __builtin_amdgcn_permlane32_swap(__float_as_uint(ls), __float_as_uint(ls), false, false); ls = __uint_as_float(x[0]) + __uint_as_float(x[1]); }
	v_sub_f32_e32 v16, v89, v16
	v_fma_f32 v16, |v16|, v91, v0
	v_sub_f32_e32 v17, v89, v17
	v_fma_f32 v0, v1, s76, v154
	v_fma_f32 v17, |v17|, v91, v0
	v_sub_f32_e32 v1, v89, v18
	v_fma_f32 v18, |v1|, v91, v2
	v_fma_f32 v2, v3, s76, v156
	v_max3_f32 v0, v32, v16, v17
	v_sub_f32_e32 v1, v89, v19
	v_fma_f32 v19, |v1|, v91, v2
	v_fma_f32 v2, v4, s76, v157
	v_fma_f32 v8, v8, s76, v163
	s_waitcnt lgkmcnt(0)
	v_sub_f32_e32 v1, v89, v20
	v_fma_f32 v20, |v1|, v91, v2
	v_fma_f32 v2, v5, s76, v158
	v_max3_f32 v0, v0, v18, v19
	v_sub_f32_e32 v1, v89, v21
	v_fma_f32 v21, |v1|, v91, v2
	s_nop 1
	v_max3_f32 v4, v0, v20, v21
	v_sub_f32_e32 v0, v89, v22
	v_fma_f32 v1, v6, s76, v159
	v_fma_f32 v22, |v0|, v91, v1
	v_fma_f32 v1, v7, s76, v162
	s_nop 0
	v_sub_f32_e32 v0, v89, v23
	v_fma_f32 v23, |v0|, v91, v1
	ds_read_b128 v[0:3], v88 offset:576
	s_nop 1
	v_max3_f32 v32, v4, v22, v23
	ds_read_b128 v[4:7], v88 offset:608
	s_waitcnt lgkmcnt(1)
	v_sub_f32_e32 v0, v89, v0
	v_fma_f32 v0, |v0|, v91, v8
	v_sub_f32_e32 v1, v89, v1
	v_fma_f32 v8, v9, s76, v212
	v_fma_f32 v1, |v1|, v91, v8
	v_sub_f32_e32 v2, v89, v2
	v_fma_f32 v9, v10, s76, v228
	v_fma_f32 v2, |v2|, v91, v9
	v_sub_f32_e32 v3, v89, v3
	v_fma_f32 v9, v11, s76, v229
	v_fma_f32 v3, |v3|, v91, v9
	s_waitcnt lgkmcnt(0)
	v_sub_f32_e32 v4, v89, v4
	v_fma_f32 v9, v12, s76, v230
	v_fma_f32 v4, |v4|, v91, v9
	v_sub_f32_e32 v5, v89, v5
	v_fma_f32 v9, v13, s76, v231
	v_fma_f32 v5, |v5|, v91, v9
	v_sub_f32_e32 v6, v89, v6
	v_fma_f32 v9, v14, s76, v232
	v_max3_f32 v8, v32, v0, v1
	v_fma_f32 v6, |v6|, v91, v9
	v_sub_f32_e32 v7, v89, v7
	v_fma_f32 v9, v15, s76, v233
	v_max3_f32 v8, v8, v2, v3
	v_fma_f32 v7, |v7|, v91, v9
	v_max3_f32 v8, v8, v4, v5
	s_nop 0
	v_max3_f32 v8, v8, v6, v7
	v_mov_b32_e32 v9, v8
	s_nop 1
	v_permlane32_swap_b32_e32 v8, v9
	v_max_f32_e32 v9, v9, v9
	v_max_f32_e32 v8, v8, v8
	v_max_f32_e32 v32, v8, v9
	v_sub_f32_e32 v8, v80, v32
	v_exp_f32_e32 v8, v8
	v_sub_f32_e32 v9, v81, v32
	v_exp_f32_e32 v9, v9
	v_sub_f32_e32 v10, v82, v32
	v_exp_f32_e32 v10, v10
	v_sub_f32_e32 v11, v83, v32
	v_exp_f32_e32 v11, v11
	v_sub_f32_e32 v12, v84, v32
	v_exp_f32_e32 v12, v12
	v_sub_f32_e32 v13, v85, v32
	v_add_f32_e32 v80, 0, v8
	v_exp_f32_e32 v13, v13
	v_sub_f32_e32 v14, v86, v32
	v_add_f32_e32 v80, v9, v80
	v_exp_f32_e32 v14, v14
	v_sub_f32_e32 v15, v87, v32
	v_add_f32_e32 v80, v10, v80
	v_exp_f32_e32 v15, v15
	v_sub_f32_e32 v72, v72, v32
	v_add_f32_e32 v80, v11, v80
	v_exp_f32_e32 v72, v72
	v_sub_f32_e32 v73, v73, v32
	v_add_f32_e32 v80, v12, v80
	v_exp_f32_e32 v73, v73
	v_sub_f32_e32 v74, v74, v32
	v_add_f32_e32 v80, v13, v80
	v_exp_f32_e32 v74, v74
	v_sub_f32_e32 v75, v75, v32
	v_add_f32_e32 v80, v14, v80
	v_exp_f32_e32 v75, v75
	v_sub_f32_e32 v76, v76, v32
	v_add_f32_e32 v80, v15, v80
	v_exp_f32_e32 v76, v76
	v_sub_f32_e32 v77, v77, v32
	v_add_f32_e32 v80, v72, v80
	v_exp_f32_e32 v77, v77
	v_sub_f32_e32 v78, v78, v32
	v_add_f32_e32 v80, v73, v80
	v_exp_f32_e32 v78, v78
	v_add_f32_e32 v80, v74, v80
	v_sub_f32_e32 v79, v79, v32
	v_add_f32_e32 v80, v75, v80
	v_exp_f32_e32 v79, v79
	v_add_f32_e32 v80, v76, v80
	v_add_f32_e32 v80, v77, v80
	v_add_f32_e32 v80, v78, v80
	v_add_f32_e32 v80, v79, v80
	v_sub_f32_e32 v64, v64, v32
	v_exp_f32_e32 v64, v64
	v_sub_f32_e32 v65, v65, v32
	v_exp_f32_e32 v65, v65
	v_sub_f32_e32 v66, v66, v32
	v_exp_f32_e32 v66, v66
	v_sub_f32_e32 v67, v67, v32
	v_exp_f32_e32 v67, v67
	v_sub_f32_e32 v68, v68, v32
	v_exp_f32_e32 v68, v68
	v_sub_f32_e32 v69, v69, v32
	v_add_f32_e32 v80, v64, v80
	v_exp_f32_e32 v69, v69
	v_sub_f32_e32 v70, v70, v32
	v_add_f32_e32 v80, v65, v80
	v_exp_f32_e32 v70, v70
	v_sub_f32_e32 v71, v71, v32
	v_add_f32_e32 v80, v66, v80
	v_exp_f32_e32 v71, v71
	v_sub_f32_e32 v56, v56, v32
	v_add_f32_e32 v80, v67, v80
	v_exp_f32_e32 v56, v56
	v_sub_f32_e32 v57, v57, v32
	v_add_f32_e32 v80, v68, v80
	v_exp_f32_e32 v57, v57
	v_sub_f32_e32 v58, v58, v32
	v_add_f32_e32 v80, v69, v80
	v_exp_f32_e32 v58, v58
	v_sub_f32_e32 v59, v59, v32
	v_add_f32_e32 v80, v70, v80
	v_exp_f32_e32 v59, v59
	v_sub_f32_e32 v60, v60, v32
	v_add_f32_e32 v80, v71, v80
	v_exp_f32_e32 v60, v60
	v_sub_f32_e32 v61, v61, v32
	v_add_f32_e32 v80, v56, v80
	v_exp_f32_e32 v61, v61
	v_sub_f32_e32 v62, v62, v32
	v_add_f32_e32 v80, v57, v80
	v_exp_f32_e32 v62, v62
	v_add_f32_e32 v80, v58, v80
	v_sub_f32_e32 v63, v63, v32
	v_add_f32_e32 v80, v59, v80
	v_exp_f32_e32 v63, v63
	v_add_f32_e32 v80, v60, v80
	v_add_f32_e32 v80, v61, v80
	v_add_f32_e32 v80, v62, v80
	v_add_f32_e32 v80, v63, v80
	v_sub_f32_e32 v40, v40, v32
	v_exp_f32_e32 v87, v40
	v_sub_f32_e32 v40, v41, v32
	v_sub_f32_e32 v48, v48, v32
	v_exp_f32_e32 v88, v40
	v_sub_f32_e32 v40, v42, v32
	v_exp_f32_e32 v81, v48
	v_sub_f32_e32 v48, v49, v32
	v_exp_f32_e32 v89, v40
	v_sub_f32_e32 v40, v43, v32
	v_exp_f32_e32 v82, v48
	v_sub_f32_e32 v48, v50, v32
	v_exp_f32_e32 v90, v40
	v_sub_f32_e32 v40, v44, v32
	v_exp_f32_e32 v83, v48
	v_sub_f32_e32 v48, v51, v32
	v_exp_f32_e32 v91, v40
	v_sub_f32_e32 v40, v45, v32
	v_exp_f32_e32 v84, v48
	v_sub_f32_e32 v48, v52, v32
	v_exp_f32_e32 v100, v40
	v_sub_f32_e32 v40, v46, v32
	v_exp_f32_e32 v85, v48
	v_sub_f32_e32 v48, v53, v32
	v_exp_f32_e32 v101, v40
	v_add_f32_e32 v40, v81, v80
	v_exp_f32_e32 v86, v48
	v_sub_f32_e32 v48, v54, v32
	v_add_f32_e32 v40, v82, v40
	v_exp_f32_e32 v54, v48
	v_sub_f32_e32 v48, v55, v32
	v_add_f32_e32 v40, v83, v40
	v_exp_f32_e32 v55, v48
	v_add_f32_e32 v40, v84, v40
	v_add_f32_e32 v40, v85, v40
	v_add_f32_e32 v40, v86, v40
	v_add_f32_e32 v40, v54, v40
	v_add_f32_e32 v40, v55, v40
	v_add_f32_e32 v40, v87, v40
	v_add_f32_e32 v40, v88, v40
	v_add_f32_e32 v40, v89, v40
	v_sub_f32_e32 v41, v47, v32
; #define SBAR() __builtin_amdgcn_sched_barrier(0)
; DI int v_rd_base(int lane) { return ((lane & 3) << 3) | (((lane >> 2) & 3) << 6) | (((lane >> 4) & 1) << 5) | (((lane >> 5) & 1) << 8); }
; DI s16x4 vtr(const char* p) { return __builtin_bit_cast(s16x4, __builtin_amdgcn_ds_read_tr16_b64_v4i16((LAS v4i16_t*)(uintptr_t)p)); }
; DI void unit(const bf16* __restrict__ QKV, const int* __restrict__ pos, bf16* __restrict__ OA, float* __restrict__ LSE,
;              int b, int h, int d, int r, int qb, float slope, char* lds) {
;     ...
;     for (int rr = 0; rr < 16; ++rr) { p[ta][rr] = __builtin_amdgcn_exp2f(p[ta][rr] - mx); ls += p[ta][rr]; if (rr == 15) SBAR(); }
;   { auto x = __builtin_amdgcn_permlane32_swap(__float_as_uint(ls), __float_as_uint(ls), false, false); ls = __uint_as_float(x[0]) + __uint_as_float(x[1]); }
;   f32x16 o[2] = {};
;   const char* vb = V_lds + att::v_rd_base(lane) + wid * 2 * 2048;
; #pragma unroll
;   for (int ta = 0; ta < 5; ++ta) {
;     bf16x8 pa0, pa1; PK4(p[ta], 0, pa0); PK4(p[ta], 8, pa1);
; #pragma unroll
;     for (int d0 = 0; d0 < 2; ++d0) {
;       const s16x4 l0 = vtr(vb + (2 * ta) * 2048 + d0 * 512), h0 = vtr(vb + (2 * ta) * 2048 + 1024 + d0 * 512);
;       const s16x4 l1 = vtr(vb + (2 * ta + 1) * 2048 + d0 * 512), h1 = vtr(vb + (2 * ta + 1) * 2048 + 1024 + d0 * 512);
;       o[d0] = __builtin_amdgcn_mfma_f32_32x32x16_bf16((bf16x8){l0[0], l0[1], l0[2], l0[3], h0[0], h0[1], h0[2], h0[3]}, pa0, o[d0], 0, 0, 0);
;       o[d0] = __builtin_amdgcn_mfma_f32_32x32x16_bf16((bf16x8){l1[0], l1[1], l1[2], l1[3], h1[0], h1[1], h1[2], h1[3]}, pa1, o[d0], 0, 0, 0);
	v_add_f32_e32 v40, v90, v40
	v_exp_f32_e32 v80, v41
	v_add_f32_e32 v40, v91, v40
	v_add_f32_e32 v40, v100, v40
	v_add_f32_e32 v40, v101, v40
	v_add_f32_e32 v40, v80, v40
	v_sub_f32_e32 v24, v24, v32
	v_exp_f32_e32 v109, v24
	v_sub_f32_e32 v24, v25, v32
	v_sub_f32_e32 v41, v116, v32
	v_exp_f32_e32 v110, v24
	v_sub_f32_e32 v24, v26, v32
	v_exp_f32_e32 v102, v41
	v_sub_f32_e32 v33, v33, v32
	v_exp_f32_e32 v111, v24
	v_sub_f32_e32 v24, v27, v32
	v_exp_f32_e32 v33, v33
	v_sub_f32_e32 v34, v34, v32
	v_exp_f32_e32 v112, v24
	v_sub_f32_e32 v24, v28, v32
	v_exp_f32_e32 v103, v34
	v_sub_f32_e32 v34, v35, v32
	v_exp_f32_e32 v113, v24
	v_sub_f32_e32 v24, v29, v32
	v_exp_f32_e32 v104, v34
	v_sub_f32_e32 v34, v36, v32
	v_exp_f32_e32 v114, v24
	v_sub_f32_e32 v24, v30, v32
	v_exp_f32_e32 v105, v34
	v_sub_f32_e32 v34, v37, v32
	v_exp_f32_e32 v115, v24
	v_add_f32_e32 v24, v102, v40
	v_exp_f32_e32 v106, v34
	v_sub_f32_e32 v34, v38, v32
	v_add_f32_e32 v24, v33, v24
	v_exp_f32_e32 v107, v34
	v_sub_f32_e32 v34, v39, v32
	v_add_f32_e32 v24, v103, v24
	v_exp_f32_e32 v108, v34
	v_add_f32_e32 v24, v104, v24
	v_add_f32_e32 v24, v105, v24
	v_add_f32_e32 v24, v106, v24
	v_add_f32_e32 v24, v107, v24
	v_add_f32_e32 v24, v108, v24
	v_add_f32_e32 v24, v109, v24
	v_add_f32_e32 v24, v110, v24
	v_add_f32_e32 v24, v111, v24
	v_sub_f32_e32 v25, v31, v32
	v_add_f32_e32 v24, v112, v24
	v_exp_f32_e32 v116, v25
	v_add_f32_e32 v24, v113, v24
	v_add_f32_e32 v24, v114, v24
	v_add_f32_e32 v24, v115, v24
	v_add_f32_e32 v24, v116, v24
	v_sub_f32_e32 v0, v0, v32
	v_exp_f32_e32 v125, v0
	v_sub_f32_e32 v0, v1, v32
	v_sub_f32_e32 v16, v16, v32
	v_exp_f32_e32 v126, v0
	v_sub_f32_e32 v0, v2, v32
	v_exp_f32_e32 v117, v16
	v_sub_f32_e32 v16, v17, v32
	v_exp_f32_e32 v127, v0
	v_sub_f32_e32 v0, v3, v32
	v_exp_f32_e32 v118, v16
	v_sub_f32_e32 v16, v18, v32
	v_exp_f32_e32 v128, v0
	v_sub_f32_e32 v0, v4, v32
	v_exp_f32_e32 v119, v16
	v_sub_f32_e32 v16, v19, v32
	v_exp_f32_e32 v129, v0
	v_sub_f32_e32 v0, v5, v32
	v_exp_f32_e32 v120, v16
	v_sub_f32_e32 v16, v20, v32
	v_exp_f32_e32 v130, v0
	v_sub_f32_e32 v0, v6, v32
	v_exp_f32_e32 v121, v16
	v_sub_f32_e32 v16, v21, v32
	v_exp_f32_e32 v131, v0
	v_add_f32_e32 v0, v117, v24
	v_exp_f32_e32 v122, v16
	v_sub_f32_e32 v16, v22, v32
	v_add_f32_e32 v0, v118, v0
	v_exp_f32_e32 v123, v16
	v_sub_f32_e32 v16, v23, v32
	v_add_f32_e32 v0, v119, v0
	v_exp_f32_e32 v124, v16
	v_add_f32_e32 v0, v120, v0
	v_add_f32_e32 v0, v121, v0
	v_add_f32_e32 v0, v122, v0
	v_add_f32_e32 v0, v123, v0
	v_add_f32_e32 v0, v124, v0
	v_add_f32_e32 v0, v125, v0
	v_add_f32_e32 v0, v126, v0
	v_add_f32_e32 v0, v127, v0
	v_sub_f32_e32 v1, v7, v32
	v_add_f32_e32 v0, v128, v0
	v_exp_f32_e32 v132, v1
	v_add_f32_e32 v0, v129, v0
	v_add_f32_e32 v0, v130, v0
	v_add_f32_e32 v0, v131, v0
	v_add_f32_e32 v133, v132, v0
	v_lshlrev_b32_e32 v0, 3, v98
	v_and_b32_e32 v1, 24, v0
	v_lshlrev_b32_e32 v2, 4, v98
	v_lshlrev_b32_e32 v3, 1, v98
	v_and_b32_e32 v2, 0xc0, v2
	v_and_b32_e32 v3, 32, v3
	v_add_u32_e32 v1, 0, v1
	v_and_b32_e32 v0, 0x100, v0
	v_add3_u32 v1, v1, v2, v3
	v_add3_u32 v99, v1, v0, v99
	v_cvt_pk_bf16_f32 v0, v8, v9
	v_cvt_pk_bf16_f32 v1, v10, v11
	v_cvt_pk_bf16_f32 v2, v12, v13
	v_cvt_pk_bf16_f32 v3, v14, v15
	v_cvt_pk_bf16_f32 v34, v72, v73
	v_cvt_pk_bf16_f32 v35, v74, v75
	v_cvt_pk_bf16_f32 v36, v76, v77
	v_cvt_pk_bf16_f32 v37, v78, v79
	ds_read_b64_tr_b16 v[4:5], v99 offset:49152
	ds_read_b64_tr_b16 v[6:7], v99 offset:50176
	v_permlane32_swap_b32_e32 v0, v2
	v_permlane32_swap_b32_e32 v1, v3
	ds_read_b64_tr_b16 v[10:11], v99 offset:50688
	ds_read_b64_tr_b16 v[8:9], v99 offset:49664
	s_waitcnt lgkmcnt(2)
	v_mfma_f32_32x32x16_bf16 v[16:31], v[4:7], v[0:3], 0
	ds_read_b64_tr_b16 v[4:5], v99 offset:51200
	ds_read_b64_tr_b16 v[6:7], v99 offset:52224
	v_permlane32_swap_b32_e32 v34, v36
	v_permlane32_swap_b32_e32 v35, v37
	ds_read_b64_tr_b16 v[40:41], v99 offset:52736
	ds_read_b64_tr_b16 v[38:39], v99 offset:51712
	v_mov_b32_e32 v72, v133
	s_waitcnt lgkmcnt(2)
	v_mfma_f32_32x32x16_bf16 v[16:31], v[4:7], v[34:37], v[16:31]
	v_permlane32_swap_b32_e32 v133, v72
	v_add_u32_e32 v73, 0xc000, v99
	v_mfma_f32_32x32x16_bf16 v[0:15], v[8:11], v[0:3], 0
	s_waitcnt lgkmcnt(0)
	v_mfma_f32_32x32x16_bf16 v[0:15], v[38:41], v[34:37], v[0:15]
	v_cvt_pk_bf16_f32 v34, v64, v65
	v_cvt_pk_bf16_f32 v35, v66, v67
	v_cvt_pk_bf16_f32 v36, v68, v69
	v_cvt_pk_bf16_f32 v37, v70, v71
	v_cvt_pk_bf16_f32 v38, v56, v57
	v_cvt_pk_bf16_f32 v39, v58, v59
	v_cvt_pk_bf16_f32 v40, v60, v61
	v_cvt_pk_bf16_f32 v41, v62, v63
	ds_read_b64_tr_b16 v[42:43], v99 offset:53248
	ds_read_b64_tr_b16 v[44:45], v99 offset:54272
	ds_read_b64_tr_b16 v[48:49], v99 offset:54784
	ds_read_b64_tr_b16 v[46:47], v99 offset:53760
	v_permlane32_swap_b32_e32 v34, v36
	v_permlane32_swap_b32_e32 v35, v37
	v_permlane32_swap_b32_e32 v38, v40
	s_waitcnt lgkmcnt(2)
; #define SBAR() __builtin_amdgcn_sched_barrier(0)
; DI s16x4 vtr(const char* p) { return __builtin_bit_cast(s16x4, __builtin_amdgcn_ds_read_tr16_b64_v4i16((LAS v4i16_t*)(uintptr_t)p)); }
; DI void unit(const bf16* __restrict__ QKV, const int* __restrict__ pos, bf16* __restrict__ OA, float* __restrict__ LSE,
;              int b, int h, int d, int r, int qb, float slope, char* lds) {
;     ...
;   for (int ta = 0; ta < 5; ++ta) {
;     bf16x8 pa0, pa1; PK4(p[ta], 0, pa0); PK4(p[ta], 8, pa1);
; #pragma unroll
;     for (int d0 = 0; d0 < 2; ++d0) {
;       const s16x4 l0 = vtr(vb + (2 * ta) * 2048 + d0 * 512), h0 = vtr(vb + (2 * ta) * 2048 + 1024 + d0 * 512);
;       const s16x4 l1 = vtr(vb + (2 * ta + 1) * 2048 + d0 * 512), h1 = vtr(vb + (2 * ta + 1) * 2048 + 1024 + d0 * 512);
;       o[d0] = __builtin_amdgcn_mfma_f32_32x32x16_bf16((bf16x8){l0[0], l0[1], l0[2], l0[3], h0[0], h0[1], h0[2], h0[3]}, pa0, o[d0], 0, 0, 0);
;       o[d0] = __builtin_amdgcn_mfma_f32_32x32x16_bf16((bf16x8){l1[0], l1[1], l1[2], l1[3], h1[0], h1[1], h1[2], h1[3]}, pa1, o[d0], 0, 0, 0);
;     }
;     SBAR();
;   }
;   if (hi == 0) LSE[(size_t)(b * SEQ + tq) * 8 + h] = (mx + __builtin_amdgcn_logf(ls)) * 0.6931471805599453f;
	v_mfma_f32_32x32x16_bf16 v[16:31], v[42:45], v[34:37], v[16:31]
	ds_read_b64_tr_b16 v[42:43], v99 offset:55296
	ds_read_b64_tr_b16 v[44:45], v99 offset:56320
	ds_read_b64_tr_b16 v[52:53], v99 offset:56832
	ds_read_b64_tr_b16 v[50:51], v99 offset:55808
	v_permlane32_swap_b32_e32 v39, v41
	s_waitcnt lgkmcnt(4)
	v_mfma_f32_32x32x16_bf16 v[0:15], v[46:49], v[34:37], v[0:15]
	s_waitcnt lgkmcnt(2)
	v_mfma_f32_32x32x16_bf16 v[16:31], v[42:45], v[38:41], v[16:31]
	s_waitcnt lgkmcnt(0)
	v_mfma_f32_32x32x16_bf16 v[0:15], v[50:53], v[38:41], v[0:15]
	v_cvt_pk_bf16_f32 v34, v81, v82
	v_cvt_pk_bf16_f32 v35, v83, v84
	v_cvt_pk_bf16_f32 v36, v85, v86
	v_cvt_pk_bf16_f32 v37, v54, v55
	v_cvt_pk_bf16_f32 v38, v87, v88
	v_cvt_pk_bf16_f32 v39, v89, v90
	v_cvt_pk_bf16_f32 v40, v91, v100
	v_cvt_pk_bf16_f32 v41, v101, v80
	ds_read_b64_tr_b16 v[42:43], v99 offset:57344
	ds_read_b64_tr_b16 v[44:45], v99 offset:58368
	ds_read_b64_tr_b16 v[48:49], v99 offset:58880
	ds_read_b64_tr_b16 v[46:47], v99 offset:57856
	v_permlane32_swap_b32_e32 v34, v36
	v_permlane32_swap_b32_e32 v35, v37
	v_permlane32_swap_b32_e32 v38, v40
	s_waitcnt lgkmcnt(2)
	v_mfma_f32_32x32x16_bf16 v[16:31], v[42:45], v[34:37], v[16:31]
	ds_read_b64_tr_b16 v[42:43], v99 offset:59392
	ds_read_b64_tr_b16 v[44:45], v99 offset:60416
	ds_read_b64_tr_b16 v[52:53], v99 offset:60928
	ds_read_b64_tr_b16 v[50:51], v99 offset:59904
	v_permlane32_swap_b32_e32 v39, v41
	s_waitcnt lgkmcnt(4)
	v_mfma_f32_32x32x16_bf16 v[0:15], v[46:49], v[34:37], v[0:15]
	s_waitcnt lgkmcnt(2)
	v_mfma_f32_32x32x16_bf16 v[16:31], v[42:45], v[38:41], v[16:31]
	s_waitcnt lgkmcnt(0)
	v_mfma_f32_32x32x16_bf16 v[0:15], v[50:53], v[38:41], v[0:15]
	v_cvt_pk_bf16_f32 v34, v102, v33
	v_cvt_pk_bf16_f32 v35, v103, v104
	v_cvt_pk_bf16_f32 v36, v105, v106
	v_cvt_pk_bf16_f32 v37, v107, v108
	v_cvt_pk_bf16_f32 v38, v109, v110
	v_cvt_pk_bf16_f32 v39, v111, v112
	v_cvt_pk_bf16_f32 v40, v113, v114
	v_cvt_pk_bf16_f32 v41, v115, v116
	ds_read_b64_tr_b16 v[42:43], v99 offset:61440
	ds_read_b64_tr_b16 v[44:45], v99 offset:62464
	ds_read_b64_tr_b16 v[48:49], v99 offset:62976
	ds_read_b64_tr_b16 v[46:47], v99 offset:61952
	v_permlane32_swap_b32_e32 v34, v36
	v_permlane32_swap_b32_e32 v35, v37
	v_permlane32_swap_b32_e32 v38, v40
	s_waitcnt lgkmcnt(2)
	v_mfma_f32_32x32x16_bf16 v[16:31], v[42:45], v[34:37], v[16:31]
	ds_read_b64_tr_b16 v[42:43], v99 offset:63488
	ds_read_b64_tr_b16 v[44:45], v99 offset:64512
	ds_read_b64_tr_b16 v[52:53], v99 offset:65024
	ds_read_b64_tr_b16 v[50:51], v99 offset:64000
	v_permlane32_swap_b32_e32 v39, v41
	s_waitcnt lgkmcnt(4)
	v_mfma_f32_32x32x16_bf16 v[0:15], v[46:49], v[34:37], v[0:15]
	s_waitcnt lgkmcnt(2)
	v_mfma_f32_32x32x16_bf16 v[16:31], v[42:45], v[38:41], v[16:31]
	s_waitcnt lgkmcnt(0)
	v_mfma_f32_32x32x16_bf16 v[0:15], v[50:53], v[38:41], v[0:15]
	v_cvt_pk_bf16_f32 v34, v117, v118
	v_cvt_pk_bf16_f32 v35, v119, v120
	v_cvt_pk_bf16_f32 v36, v121, v122
	v_cvt_pk_bf16_f32 v37, v123, v124
	v_cvt_pk_bf16_f32 v38, v125, v126
	v_cvt_pk_bf16_f32 v39, v127, v128
	v_cvt_pk_bf16_f32 v40, v129, v130
	v_cvt_pk_bf16_f32 v41, v131, v132
	ds_read_b64_tr_b16 v[42:43], v73 offset:16384
	ds_read_b64_tr_b16 v[44:45], v73 offset:17408
	ds_read_b64_tr_b16 v[48:49], v73 offset:17920
	ds_read_b64_tr_b16 v[46:47], v73 offset:16896
	v_permlane32_swap_b32_e32 v34, v36
	v_permlane32_swap_b32_e32 v35, v37
	v_permlane32_swap_b32_e32 v38, v40
	s_waitcnt lgkmcnt(2)
	v_mfma_f32_32x32x16_bf16 v[16:31], v[42:45], v[34:37], v[16:31]
	ds_read_b64_tr_b16 v[42:43], v73 offset:18432
	ds_read_b64_tr_b16 v[44:45], v73 offset:19456
	ds_read_b64_tr_b16 v[52:53], v73 offset:19968
	ds_read_b64_tr_b16 v[50:51], v73 offset:18944
	v_permlane32_swap_b32_e32 v39, v41
	s_waitcnt lgkmcnt(4)
	v_mfma_f32_32x32x16_bf16 v[0:15], v[46:49], v[34:37], v[0:15]
	s_waitcnt lgkmcnt(2)
	v_mfma_f32_32x32x16_bf16 v[16:31], v[42:45], v[38:41], v[16:31]
	s_waitcnt lgkmcnt(0)
	v_mfma_f32_32x32x16_bf16 v[0:15], v[50:53], v[38:41], v[0:15]
	v_add_f32_e32 v33, v133, v72
	v_cmp_gt_u32_e32 vcc, 32, v98
	s_and_saveexec_b64 s[2:3], vcc
	s_cbranch_execz .LBB0_857
	v_log_f32_e32 v34, v33
	s_lshl_b64 s[4:5], s[14:15], 20
	s_add_u32 s4, s13, s4
	s_addc_u32 s5, s38, s5
	v_add_f32_e32 v32, v32, v34
	v_lshlrev_b64 v[34:35], 5, v[94:95]
	v_lshl_add_u64 v[34:35], s[4:5], 0, v[34:35]
	s_lshl_b32 s8, s48, 2
	v_mul_f32_e32 v32, 0x3f317218, v32
	v_lshl_add_u64 v[34:35], v[34:35], 0, s[8:9]
	global_store_dword v[34:35], v32, off
	s_branch .LBB0_857

;     DI void operator()(const f32x4 (&acc)[2][2][4][2], const Unit& u, int wr, int wc, int fr, int fq) const {
;         const int row0 = u.pm * 256 + wr * 64 + fr, col0 = u.pn * 128 + wc * 32 + 8 * fq;
;         float ssv[8];
; #pragma unroll
;         for (int i = 0; i < 8; ++i) ssv[i] = SS[(size_t)(row0 + (i >> 2) * 128 + (i & 3) * 16)];
.LBB0_1379:
	s_add_u32 s8, s14, 0xfc00000
	s_addc_u32 s9, s15, 0
	s_add_u32 s14, s14, 0x1f600000
	s_addc_u32 s15, s15, 0
	s_lshl_b32 s16, s16, 5
	s_and_b32 s30, s16, 0x60
	s_mov_b64 s[16:17], 0x80
	s_add_i32 m0, s43, 0x18000
	v_lshl_add_u64 v[6:7], v[6:7], 0, s[16:17]
	s_lshl_b32 s19, s5, 13
	s_lshl_b32 s31, s30, 7
	s_waitcnt vmcnt(2)
	s_barrier
	global_load_lds_dwordx4 v[6:7], off
	v_lshl_add_u64 v[4:5], v[4:5], 0, s[16:17]
	s_add_i32 m0, s43, 0x1a000
	s_add_i32 s56, s43, 0x8000
	s_add_i32 s57, s43, 0xa000
	global_load_lds_dwordx4 v[4:5], off
	v_lshl_add_u64 v[0:1], v[0:1], 0, s[16:17]
	s_mov_b32 m0, s56
	s_add_u32 s20, s46, 0x40080
	global_load_lds_dwordx4 v[0:1], off
	v_lshl_add_u64 v[0:1], v[2:3], 0, s[16:17]
	s_mov_b32 m0, s57
	s_addc_u32 s21, s47, 0
	global_load_lds_dwordx4 v[0:1], off
	s_add_i32 m0, s43, 0x1c000
	v_lshl_add_u64 v[0:1], s[20:21], 0, v[132:133]
	global_load_lds_dwordx4 v[0:1], off
	v_lshl_add_u64 v[0:1], s[20:21], 0, v[128:129]
	s_add_i32 m0, s43, 0x1e000
	s_cmpk_lt_u32 s18, 0x100
	global_load_lds_dwordx4 v[0:1], off
	v_lshrrev_b32_e32 v1, 1, v9
	v_and_b32_e32 v1, 24, v1
	v_and_b32_e32 v0, 15, v9
	v_lshlrev_b32_e32 v2, 1, v1
	v_lshl_or_b32 v146, s5, 6, v0
	v_lshl_or_b32 v0, v0, 6, v2
	v_lshlrev_b32_e32 v2, 2, v9
	v_and_b32_e32 v2, 32, v2
	v_bitop3_b32 v3, v0, s19, v2 bitop3:0xde
	v_bitop3_b32 v147, v0, s31, v2 bitop3:0xde
	v_lshlrev_b32_e32 v0, 14, v13
	v_and_b32_e32 v0, 0xffff8000, v0
	v_or_b32_e32 v148, s30, v1
	v_lshl_add_u32 v0, v12, 11, v0
	v_and_b32_e32 v1, 1, v13
	v_lshl_or_b32 v0, v1, 6, v0
	v_lshl_add_u32 v136, v14, 1, v0
	v_lshlrev_b32_e32 v0, 14, v8
	v_and_b32_e32 v0, 0xffff8000, v0
	s_waitcnt vmcnt(6)
	v_lshl_add_u32 v0, v10, 11, v0
	v_and_b32_e32 v1, 1, v8
	s_cselect_b64 s[18:19], -1, 0
	v_lshl_or_b32 v0, v1, 6, v0
	s_add_i32 s58, 0, 0x10000
	s_add_i32 s59, 0, 0x14000
	s_sext_i32_i16 s61, s4
	v_mov_b32_e32 v137, v133
	v_lshl_add_u32 v138, v11, 1, v0
	v_mov_b32_e32 v139, v133
	v_mov_b64_e32 v[140:141], 0xb00
	v_mov_b64_e32 v[142:143], 0xaff
	v_add_u32_e32 v149, s58, v147
	v_add_u32_e32 v150, s59, v147
	v_add_u32_e32 v151, 0, v3
	v_mov_b32_e32 v152, 0x358637bd
	s_movk_i32 s60, 0x1600
	v_lshl_add_u32 v234, s42, 8, v146
	v_ashrrev_i32_e32 v235, 31, v234
	v_lshl_add_u64 v[234:235], v[234:235], 2, s[14:15]
	global_load_dword v226, v[234:235], off
	global_load_dword v227, v[234:235], off offset:64
	global_load_dword v228, v[234:235], off offset:128
	global_load_dword v229, v[234:235], off offset:192
	global_load_dword v230, v[234:235], off offset:512
	global_load_dword v231, v[234:235], off offset:576
	global_load_dword v232, v[234:235], off offset:640
	global_load_dword v233, v[234:235], off offset:704
	s_barrier
	s_branch .LBB0_1382

; DI u32x4 pack8(const f32x4 v0, const f32x4 v1) { u32x4 w; w.x = cvt_pk_bf16(v0[0], v0[1]); w.y = cvt_pk_bf16(v0[2], v0[3]); w.z = cvt_pk_bf16(v1[0], v1[1]); w.w = cvt_pk_bf16(v1[2], v1[3]); return w; }
;     DI void operator()(const f32x4 (&acc)[2][2][4][2], const Unit& u, int wr, int wc, int fr, int fq) const {
;     ...
;         float ssv[8];
; #pragma unroll
;         for (int i = 0; i < 8; ++i) ssv[i] = SS[(size_t)(row0 + (i >> 2) * 128 + (i & 3) * 16)];
; #pragma unroll
;         for (int ai = 0; ai < 2; ++ai)
; #pragma unroll
;             for (int m = 0; m < 4; ++m) {
;                 const size_t row = (size_t)(row0 + ai * 128 + m * 16);
;                 const float rs = __builtin_amdgcn_rsqf(ssv[ai * 4 + m] * (1.0f / 1024.0f) + EPS);
;                 const float c1 = -rs * 1.4426950408889634f, rs2 = rs * rs;
;                 f32x4 o[2];
; #pragma unroll
;                 for (int n = 0; n < 2; ++n)
; #pragma unroll
;                     for (int j = 0; j < 4; ++j) { const float ga = acc[ai][0][m][n][j], ua = acc[ai][1][m][n][j];
;                         o[n][j] = (ga * ua) * (rs2 * __builtin_amdgcn_rcpf(1.0f + __builtin_amdgcn_exp2f(ga * c1))); }
;                 __builtin_nontemporal_store(pack8(o[0], o[1]), (u32x4*)(GU + row * DFF + col0));
;             }
.LBB0_1388:
	v_lshl_add_u32 v144, s42, 8, v146
	v_ashrrev_i32_e32 v145, 31, v144
	v_lshl_add_u64 v[154:155], v[144:145], 2, s[14:15]
	v_mov_b32_e32 v145, v226
	v_mov_b32_e32 v153, v227
	v_mov_b32_e32 v160, v124
	v_mov_b32_e32 v164, v126
	v_mov_b32_e32 v178, v104
	v_mov_b32_e32 v182, v228
	v_mov_b32_e32 v183, v229
	v_mov_b32_e32 v184, v230
	v_mov_b32_e32 v126, v231
	v_mov_b32_e32 v124, v232
	v_mov_b32_e32 v104, v233
	s_and_b64 s[30:31], s[4:5], exec
	s_cselect_b32 s30, s36, s42
	v_lshl_add_u32 v234, s30, 8, v146
	v_ashrrev_i32_e32 v235, 31, v234
	v_lshl_add_u64 v[234:235], v[234:235], 2, s[14:15]
	global_load_dword v226, v[234:235], off
	global_load_dword v227, v[234:235], off offset:64
	global_load_dword v228, v[234:235], off offset:128
	global_load_dword v229, v[234:235], off offset:192
	global_load_dword v230, v[234:235], off offset:512
	global_load_dword v231, v[234:235], off offset:576
	global_load_dword v232, v[234:235], off offset:640
	global_load_dword v233, v[234:235], off offset:704
	v_lshl_or_b32 v156, s61, 7, v148
	v_ashrrev_i32_e32 v157, 31, v156
	v_mov_b32_e32 v172, v122
	v_mov_b32_e32 v174, v123
	v_lshlrev_b64 v[122:123], 1, v[156:157]
	v_mov_b32_e32 v158, v116
	v_mov_b32_e32 v176, v108
	v_mov_b32_e32 v168, v120
	v_mov_b32_e32 v170, v121
	v_mov_b64_e32 v[120:121], s[8:9]
	v_mad_i64_i32 v[180:181], s[30:31], v144, s60, v[120:121]
	v_lshl_add_u64 v[154:155], v[180:181], 0, v[122:123]
	v_mov_b32_e32 v162, v125
	v_mov_b32_e32 v166, v127
	v_or_b32_e32 v127, 16, v144
	v_add_u32_e32 v125, 0x80, v144
	s_andn2_b64 vcc, exec, s[4:5]
	s_mov_b64 s[4:5], -1
	v_fmamk_f32 v145, v145, 0x3a800000, v152
	v_rsq_f32_e32 v145, v145
	v_fmamk_f32 v153, v153, 0x3a800000, v152
	v_rsq_f32_e32 v153, v153
	v_mul_f32_e32 v156, 0xbfb8aa3b, v145
	v_mul_f32_e32 v159, v145, v145
	v_mul_f32_e32 v145, 0xbfb8aa3b, v153
	v_mul_f32_e32 v116, v116, v156
	v_mul_f32_e32 v177, v153, v153
	v_mul_f32_e32 v153, v117, v156
	v_mul_f32_e32 v161, v119, v156
	v_mul_f32_e32 v163, v112, v156
	v_mul_f32_e32 v167, v114, v156
	v_mul_f32_e32 v108, v108, v145
	v_exp_f32_e32 v116, v116
	v_mul_f32_e32 v157, v118, v156
	v_mul_f32_e32 v169, v109, v145
	v_exp_f32_e32 v153, v153
	v_exp_f32_e32 v161, v161
	v_exp_f32_e32 v163, v163
	v_exp_f32_e32 v167, v167
	v_exp_f32_e32 v108, v108
	v_mul_f32_e32 v165, v113, v156
	v_exp_f32_e32 v157, v157
	v_exp_f32_e32 v169, v169
	v_exp_f32_e32 v165, v165
	v_add_f32_e32 v116, 1.0, v116
	v_add_f32_e32 v153, 1.0, v153
	v_add_f32_e32 v171, 1.0, v161
	v_add_f32_e32 v173, 1.0, v163
	v_add_f32_e32 v179, 1.0, v167
	v_add_f32_e32 v108, 1.0, v108
	v_rcp_f32_e32 v161, v116
	v_mul_f32_e32 v156, v115, v156
	v_add_f32_e32 v157, 1.0, v157
	v_add_f32_e32 v180, 1.0, v169
	v_rcp_f32_e32 v163, v153
	v_rcp_f32_e32 v169, v173
	v_rcp_f32_e32 v173, v179
	v_rcp_f32_e32 v179, v108
	v_exp_f32_e32 v156, v156
	v_add_f32_e32 v175, 1.0, v165
	v_rcp_f32_e32 v165, v157
	v_rcp_f32_e32 v167, v171
	v_mul_f32_e32 v160, v158, v160
	v_mul_f32_e32 v161, v159, v161
	v_mov_b32_e32 v158, v117
	v_rcp_f32_e32 v171, v175
	v_mul_f32_e32 v116, v176, v178
	v_mul_f32_e32 v117, v177, v179
	v_mov_b32_e32 v176, v109
	v_mul_f32_e32 v108, v158, v162
	v_mul_f32_e32 v109, v159, v163
	v_add_f32_e32 v156, 1.0, v156
	v_mul_f32_e32 v116, v116, v117
	v_mul_f32_e32 v117, v108, v109
	v_mul_f32_e32 v108, v118, v164
	v_mul_f32_e32 v109, v159, v165
	v_rcp_f32_e32 v175, v156
	v_mul_f32_e32 v118, v108, v109
	v_mul_f32_e32 v108, v119, v166
	v_mul_f32_e32 v109, v159, v167
	v_mov_b32_e32 v158, v112
	v_mul_f32_e32 v153, v160, v161
	v_cvt_pk_bf16_f32 v112, v153, v117
	v_mul_f32_e32 v117, v108, v109
	v_mul_f32_e32 v108, v158, v168
	v_mul_f32_e32 v109, v159, v169
	v_mul_f32_e32 v119, v108, v109
	v_mul_f32_e32 v108, v113, v170
	v_mul_f32_e32 v109, v159, v171
	v_mov_b32_e32 v158, v114
	v_mul_f32_e32 v114, v108, v109
	v_mul_f32_e32 v108, v158, v172
	v_mul_f32_e32 v109, v159, v173
	v_mov_b32_e32 v158, v115
	v_mul_f32_e32 v115, v108, v109
	v_mul_f32_e32 v108, v158, v174
	v_mul_f32_e32 v109, v159, v175
	v_rcp_f32_e32 v157, v180
	v_mul_f32_e32 v108, v108, v109
	v_cvt_pk_bf16_f32 v115, v115, v108
	v_mul_f32_e32 v108, v110, v145
	v_cvt_pk_bf16_f32 v113, v118, v117
	v_cvt_pk_bf16_f32 v114, v119, v114
	global_store_dwordx4 v[154:155], v[112:115], off nt
	v_mov_b32_e32 v156, v105
	s_nop 0
	v_exp_f32_e32 v112, v108
	v_mul_f32_e32 v108, v176, v105
	v_mul_f32_e32 v109, v177, v157
	v_mov_b32_e32 v176, v110
	v_mul_f32_e32 v105, v108, v109
	v_add_f32_e32 v108, 1.0, v112
	v_rcp_f32_e32 v109, v108
	v_mul_f32_e32 v108, v111, v145
	v_exp_f32_e32 v110, v108
	v_mul_f32_e32 v108, v176, v106
	v_mul_f32_e32 v109, v177, v109
	v_add_f32_e32 v106, 1.0, v110
	v_mul_f32_e32 v112, v108, v109
	v_rcp_f32_e32 v109, v106
	v_mul_f32_e32 v106, v100, v145
	v_exp_f32_e32 v110, v106
	v_mul_f32_e32 v106, v111, v107
	v_mul_f32_e32 v107, v177, v109
	v_mov_b32_e32 v176, v100
	v_mul_f32_e32 v108, v106, v107
	v_add_f32_e32 v106, 1.0, v110
	v_mul_f32_e32 v100, v101, v145
	v_rcp_f32_e32 v107, v106
	v_exp_f32_e32 v100, v100
	v_mul_f32_e32 v106, v176, v96
	v_mul_f32_e32 v107, v177, v107
	v_add_f32_e32 v96, 1.0, v100
	v_mul_f32_e32 v109, v106, v107
	v_rcp_f32_e32 v107, v96
	v_mul_f32_e32 v96, v102, v145
	v_exp_f32_e32 v100, v96
	v_mul_f32_e32 v96, v101, v97
	v_mul_f32_e32 v97, v177, v107
	v_mul_f32_e32 v106, v96, v97
	v_add_f32_e32 v96, 1.0, v100
	v_rcp_f32_e32 v97, v96
	v_mul_f32_e32 v96, v103, v145
	v_exp_f32_e32 v100, v96
	v_mul_f32_e32 v96, v102, v98
	v_mul_f32_e32 v97, v177, v97
	v_mov_b32_e32 v176, v103
	v_add_f32_e32 v98, 1.0, v100
	v_rcp_f32_e32 v101, v98
	v_mul_f32_e32 v102, v96, v97
	v_cvt_pk_bf16_f32 v98, v109, v106
	v_mul_f32_e32 v96, v103, v99
	v_mul_f32_e32 v97, v177, v101
; DI u32x4 pack8(const f32x4 v0, const f32x4 v1) { u32x4 w; w.x = cvt_pk_bf16(v0[0], v0[1]); w.y = cvt_pk_bf16(v0[2], v0[3]); w.z = cvt_pk_bf16(v1[0], v1[1]); w.w = cvt_pk_bf16(v1[2], v1[3]); return w; }
;     DI void operator()(const f32x4 (&acc)[2][2][4][2], const Unit& u, int wr, int wc, int fr, int fq) const {
;     ...
; #pragma unroll
;         for (int ai = 0; ai < 2; ++ai)
; #pragma unroll
;             for (int m = 0; m < 4; ++m) {
;                 const size_t row = (size_t)(row0 + ai * 128 + m * 16);
;                 const float rs = __builtin_amdgcn_rsqf(ssv[ai * 4 + m] * (1.0f / 1024.0f) + EPS);
;                 const float c1 = -rs * 1.4426950408889634f, rs2 = rs * rs;
;                 f32x4 o[2];
; #pragma unroll
;                 for (int n = 0; n < 2; ++n)
; #pragma unroll
;                     for (int j = 0; j < 4; ++j) { const float ga = acc[ai][0][m][n][j], ua = acc[ai][1][m][n][j];
;                         o[n][j] = (ga * ua) * (rs2 * __builtin_amdgcn_rcpf(1.0f + __builtin_amdgcn_exp2f(ga * c1))); }
;                 __builtin_nontemporal_store(pack8(o[0], o[1]), (u32x4*)(GU + row * DFF + col0));
;             }
	v_fmamk_f32 v100, v182, 0x3a800000, v152
	v_mul_f32_e32 v99, v96, v97
	v_cvt_pk_bf16_f32 v99, v102, v99
	v_rsq_f32_e32 v102, v100
	v_cvt_pk_bf16_f32 v96, v116, v105
	v_mad_i64_i32 v[100:101], s[30:31], v127, s60, v[120:121]
	v_mul_f32_e32 v103, 0xbfb8aa3b, v102
	v_mul_f32_e32 v105, v92, v103
	v_exp_f32_e32 v105, v105
	v_lshl_add_u64 v[100:101], v[100:101], 0, v[122:123]
	v_cvt_pk_bf16_f32 v97, v112, v108
	global_store_dwordx4 v[100:101], v[96:99], off nt
	v_or_b32_e32 v100, 32, v144
	s_nop 0
	v_add_f32_e32 v96, 1.0, v105
	v_rcp_f32_e32 v99, v96
	v_mov_b32_e32 v96, v92
	v_mul_f32_e32 v92, v93, v103
	v_exp_f32_e32 v92, v92
	v_mul_f32_e32 v97, v102, v102
	v_mul_f32_e32 v98, v96, v88
	v_mul_f32_e32 v99, v97, v99
	v_add_f32_e32 v88, 1.0, v92
	v_mul_f32_e32 v101, v98, v99
	v_rcp_f32_e32 v99, v88
	v_mul_f32_e32 v88, v94, v103
	v_exp_f32_e32 v92, v88
	v_mov_b32_e32 v98, v89
	v_mul_f32_e32 v88, v93, v89
	v_mul_f32_e32 v89, v97, v99
	v_mul_f32_e32 v93, v88, v89
	v_add_f32_e32 v88, 1.0, v92
	v_rcp_f32_e32 v89, v88
	v_mul_f32_e32 v88, v95, v103
	v_exp_f32_e32 v92, v88
	v_mul_f32_e32 v88, v94, v90
	v_mul_f32_e32 v89, v97, v89
	v_mul_f32_e32 v90, v88, v89
	v_add_f32_e32 v88, 1.0, v92
	v_rcp_f32_e32 v89, v88
	v_mul_f32_e32 v88, v84, v103
	v_exp_f32_e32 v92, v88
	v_mul_f32_e32 v88, v95, v91
	v_mul_f32_e32 v89, v97, v89
	v_mov_b32_e32 v96, v84
	v_mul_f32_e32 v91, v88, v89
	v_add_f32_e32 v88, 1.0, v92
	v_mul_f32_e32 v84, v85, v103
	v_rcp_f32_e32 v89, v88
	v_exp_f32_e32 v84, v84
	v_mul_f32_e32 v88, v96, v80
	v_mul_f32_e32 v89, v97, v89
	v_add_f32_e32 v80, 1.0, v84
	v_mul_f32_e32 v92, v88, v89
	v_rcp_f32_e32 v89, v80
	v_mul_f32_e32 v80, v86, v103
	v_exp_f32_e32 v84, v80
	v_mul_f32_e32 v80, v85, v81
	v_mul_f32_e32 v81, v97, v89
	v_mul_f32_e32 v88, v80, v81
	v_add_f32_e32 v80, 1.0, v84
	v_rcp_f32_e32 v81, v80
	v_mul_f32_e32 v80, v87, v103
	v_exp_f32_e32 v84, v80
	v_mul_f32_e32 v80, v86, v82
	v_mul_f32_e32 v81, v97, v81
	v_mov_b32_e32 v96, v87
	v_add_f32_e32 v82, 1.0, v84
	v_rcp_f32_e32 v85, v82
	v_mul_f32_e32 v86, v80, v81
	v_cvt_pk_bf16_f32 v82, v92, v88
	v_mul_f32_e32 v80, v87, v83
	v_mul_f32_e32 v81, v97, v85
	v_fmamk_f32 v84, v183, 0x3a800000, v152
	v_mul_f32_e32 v83, v80, v81
	v_cvt_pk_bf16_f32 v83, v86, v83
	v_rsq_f32_e32 v86, v84
	v_mad_i64_i32 v[84:85], s[30:31], v100, s60, v[120:121]
	v_cvt_pk_bf16_f32 v80, v101, v93
	v_mul_f32_e32 v87, 0xbfb8aa3b, v86
	v_mul_f32_e32 v88, v76, v87
	v_exp_f32_e32 v88, v88
	v_lshl_add_u64 v[84:85], v[84:85], 0, v[122:123]
	v_cvt_pk_bf16_f32 v81, v90, v91
	global_store_dwordx4 v[84:85], v[80:83], off nt
	v_or_b32_e32 v84, 48, v144
	s_nop 0
	v_add_f32_e32 v80, 1.0, v88
	v_rcp_f32_e32 v83, v80
	v_mov_b32_e32 v80, v76
	v_mul_f32_e32 v76, v77, v87
	v_exp_f32_e32 v76, v76
	v_mul_f32_e32 v81, v86, v86
	v_mul_f32_e32 v82, v80, v72
	v_mul_f32_e32 v83, v81, v83
	v_add_f32_e32 v72, 1.0, v76
	v_mul_f32_e32 v85, v82, v83
	v_rcp_f32_e32 v83, v72
	v_mul_f32_e32 v72, v78, v87
	v_exp_f32_e32 v76, v72
	v_mov_b32_e32 v82, v73
	v_mul_f32_e32 v72, v77, v73
	v_mul_f32_e32 v73, v81, v83
	v_mul_f32_e32 v77, v72, v73
	v_add_f32_e32 v72, 1.0, v76
	v_rcp_f32_e32 v73, v72
	v_mul_f32_e32 v72, v79, v87
	v_exp_f32_e32 v76, v72
	v_mul_f32_e32 v72, v78, v74
	v_mul_f32_e32 v73, v81, v73
	v_mul_f32_e32 v74, v72, v73
	v_add_f32_e32 v72, 1.0, v76
	v_rcp_f32_e32 v73, v72
	v_mul_f32_e32 v72, v68, v87
	v_exp_f32_e32 v76, v72
	v_mul_f32_e32 v72, v79, v75
	v_mul_f32_e32 v73, v81, v73
	v_mov_b32_e32 v80, v68
	v_mul_f32_e32 v75, v72, v73
	v_add_f32_e32 v72, 1.0, v76
	v_mul_f32_e32 v68, v69, v87
	v_rcp_f32_e32 v73, v72
	v_exp_f32_e32 v68, v68
	v_mul_f32_e32 v72, v80, v64
	v_mul_f32_e32 v73, v81, v73
	v_add_f32_e32 v64, 1.0, v68
	v_mul_f32_e32 v76, v72, v73
	v_rcp_f32_e32 v73, v64
	v_mul_f32_e32 v64, v70, v87
	v_exp_f32_e32 v68, v64
	v_mul_f32_e32 v64, v69, v65
	v_mul_f32_e32 v65, v81, v73
	v_mul_f32_e32 v72, v64, v65
	v_add_f32_e32 v64, 1.0, v68
	v_rcp_f32_e32 v65, v64
	v_mul_f32_e32 v64, v71, v87
	v_exp_f32_e32 v68, v64
	v_mul_f32_e32 v64, v70, v66
	v_mul_f32_e32 v65, v81, v65
	v_mov_b32_e32 v80, v71
	v_add_f32_e32 v66, 1.0, v68
	v_rcp_f32_e32 v69, v66
	v_mul_f32_e32 v70, v64, v65
	v_cvt_pk_bf16_f32 v66, v76, v72
	v_mul_f32_e32 v64, v71, v67
	v_mul_f32_e32 v65, v81, v69
	v_fmamk_f32 v68, v184, 0x3a800000, v152
	v_rsq_f32_e32 v71, v68
	v_mul_f32_e32 v67, v64, v65
	v_cvt_pk_bf16_f32 v67, v70, v67
	v_mad_i64_i32 v[68:69], s[30:31], v84, s60, v[120:121]
	v_mul_f32_e32 v70, 0xbfb8aa3b, v71
	v_mul_f32_e32 v72, v60, v70
	v_exp_f32_e32 v72, v72
	v_cvt_pk_bf16_f32 v64, v85, v77
	v_lshl_add_u64 v[68:69], v[68:69], 0, v[122:123]
	v_cvt_pk_bf16_f32 v65, v74, v75
	global_store_dwordx4 v[68:69], v[64:67], off nt
	s_nop 1
	v_add_f32_e32 v64, 1.0, v72
	v_rcp_f32_e32 v67, v64
	v_mov_b32_e32 v64, v60
	v_mul_f32_e32 v60, v61, v70
	v_exp_f32_e32 v60, v60
	v_mul_f32_e32 v65, v71, v71
	v_mul_f32_e32 v66, v64, v56
	v_mul_f32_e32 v67, v65, v67
	v_add_f32_e32 v56, 1.0, v60
	v_mul_f32_e32 v68, v66, v67
	v_rcp_f32_e32 v67, v56
	v_mul_f32_e32 v56, v62, v70
	v_exp_f32_e32 v60, v56
	v_mov_b32_e32 v66, v57
	v_mul_f32_e32 v56, v61, v57
	v_mul_f32_e32 v57, v65, v67
	v_mul_f32_e32 v61, v56, v57
	v_add_f32_e32 v56, 1.0, v60
	v_rcp_f32_e32 v57, v56
	v_mul_f32_e32 v56, v63, v70
	v_exp_f32_e32 v60, v56
	v_mul_f32_e32 v56, v62, v58
	v_mul_f32_e32 v57, v65, v57
	v_mul_f32_e32 v58, v56, v57
	v_add_f32_e32 v56, 1.0, v60
	v_rcp_f32_e32 v57, v56
	v_mul_f32_e32 v56, v52, v70
	v_exp_f32_e32 v60, v56
	v_mul_f32_e32 v56, v63, v59
	v_mul_f32_e32 v57, v65, v57
	v_mov_b32_e32 v64, v52
	v_mul_f32_e32 v59, v56, v57
	v_add_f32_e32 v56, 1.0, v60
	v_mul_f32_e32 v52, v53, v70
	v_rcp_f32_e32 v57, v56
	v_exp_f32_e32 v52, v52
; DI u32x4 pack8(const f32x4 v0, const f32x4 v1) { u32x4 w; w.x = cvt_pk_bf16(v0[0], v0[1]); w.y = cvt_pk_bf16(v0[2], v0[3]); w.z = cvt_pk_bf16(v1[0], v1[1]); w.w = cvt_pk_bf16(v1[2], v1[3]); return w; }
;     DI void operator()(const f32x4 (&acc)[2][2][4][2], const Unit& u, int wr, int wc, int fr, int fq) const {
;     ...
; #pragma unroll
;         for (int ai = 0; ai < 2; ++ai)
; #pragma unroll
;             for (int m = 0; m < 4; ++m) {
;                 const size_t row = (size_t)(row0 + ai * 128 + m * 16);
;                 const float rs = __builtin_amdgcn_rsqf(ssv[ai * 4 + m] * (1.0f / 1024.0f) + EPS);
;                 const float c1 = -rs * 1.4426950408889634f, rs2 = rs * rs;
;                 f32x4 o[2];
; #pragma unroll
;                 for (int n = 0; n < 2; ++n)
; #pragma unroll
;                     for (int j = 0; j < 4; ++j) { const float ga = acc[ai][0][m][n][j], ua = acc[ai][1][m][n][j];
;                         o[n][j] = (ga * ua) * (rs2 * __builtin_amdgcn_rcpf(1.0f + __builtin_amdgcn_exp2f(ga * c1))); }
;                 __builtin_nontemporal_store(pack8(o[0], o[1]), (u32x4*)(GU + row * DFF + col0));
;             }
	v_mul_f32_e32 v56, v64, v48
	v_mul_f32_e32 v57, v65, v57
	v_add_f32_e32 v48, 1.0, v52
	v_mul_f32_e32 v60, v56, v57
	v_rcp_f32_e32 v57, v48
	v_mul_f32_e32 v48, v54, v70
	v_exp_f32_e32 v52, v48
	v_mul_f32_e32 v48, v53, v49
	v_mul_f32_e32 v49, v65, v57
	v_mul_f32_e32 v56, v48, v49
	v_add_f32_e32 v48, 1.0, v52
	v_rcp_f32_e32 v49, v48
	v_mul_f32_e32 v48, v55, v70
	v_exp_f32_e32 v52, v48
	v_mul_f32_e32 v48, v54, v50
	v_mul_f32_e32 v49, v65, v49
	v_mov_b32_e32 v64, v55
	v_add_f32_e32 v50, 1.0, v52
	v_rcp_f32_e32 v53, v50
	v_mul_f32_e32 v54, v48, v49
	v_cvt_pk_bf16_f32 v50, v60, v56
	v_mul_f32_e32 v48, v55, v51
	v_mul_f32_e32 v49, v65, v53
	v_fmamk_f32 v52, v126, 0x3a800000, v152
	v_mul_f32_e32 v51, v48, v49
	v_cvt_pk_bf16_f32 v51, v54, v51
	v_rsq_f32_e32 v54, v52
	v_mad_i64_i32 v[52:53], s[30:31], v125, s60, v[120:121]
	v_cvt_pk_bf16_f32 v48, v68, v61
	v_mul_f32_e32 v55, 0xbfb8aa3b, v54
	v_mul_f32_e32 v56, v44, v55
	v_exp_f32_e32 v56, v56
	v_lshl_add_u64 v[52:53], v[52:53], 0, v[122:123]
	v_cvt_pk_bf16_f32 v49, v58, v59
	global_store_dwordx4 v[52:53], v[48:51], off nt
	v_add_u32_e32 v52, 0x90, v144
	s_nop 0
	v_add_f32_e32 v48, 1.0, v56
	v_rcp_f32_e32 v51, v48
	v_mov_b32_e32 v48, v44
	v_mul_f32_e32 v44, v45, v55
	v_exp_f32_e32 v44, v44
	v_mul_f32_e32 v49, v54, v54
	v_mul_f32_e32 v50, v48, v40
	v_mul_f32_e32 v51, v49, v51
	v_add_f32_e32 v40, 1.0, v44
	v_mul_f32_e32 v53, v50, v51
	v_rcp_f32_e32 v51, v40
	v_mul_f32_e32 v40, v46, v55
	v_exp_f32_e32 v44, v40
	v_mov_b32_e32 v50, v41
	v_mul_f32_e32 v40, v45, v41
	v_mul_f32_e32 v41, v49, v51
	v_mul_f32_e32 v45, v40, v41
	v_add_f32_e32 v40, 1.0, v44
	v_rcp_f32_e32 v41, v40
	v_mul_f32_e32 v40, v47, v55
	v_exp_f32_e32 v44, v40
	v_mul_f32_e32 v40, v46, v42
	v_mul_f32_e32 v41, v49, v41
	v_mul_f32_e32 v42, v40, v41
	v_add_f32_e32 v40, 1.0, v44
	v_rcp_f32_e32 v41, v40
	v_mul_f32_e32 v40, v36, v55
	v_exp_f32_e32 v44, v40
	v_mul_f32_e32 v40, v47, v43
	v_mul_f32_e32 v41, v49, v41
	v_mov_b32_e32 v48, v36
	v_mul_f32_e32 v43, v40, v41
	v_add_f32_e32 v40, 1.0, v44
	v_mul_f32_e32 v36, v37, v55
	v_rcp_f32_e32 v41, v40
	v_exp_f32_e32 v36, v36
	v_mul_f32_e32 v40, v48, v32
	v_mul_f32_e32 v41, v49, v41
	v_add_f32_e32 v32, 1.0, v36
	v_mul_f32_e32 v44, v40, v41
	v_rcp_f32_e32 v41, v32
	v_mul_f32_e32 v32, v38, v55
	v_exp_f32_e32 v36, v32
	v_mul_f32_e32 v32, v37, v33
	v_mul_f32_e32 v33, v49, v41
	v_mul_f32_e32 v40, v32, v33
	v_add_f32_e32 v32, 1.0, v36
	v_rcp_f32_e32 v33, v32
	v_mul_f32_e32 v32, v39, v55
	v_exp_f32_e32 v36, v32
	v_mul_f32_e32 v32, v38, v34
	v_mul_f32_e32 v33, v49, v33
	v_mov_b32_e32 v48, v39
	v_add_f32_e32 v34, 1.0, v36
	v_rcp_f32_e32 v37, v34
	v_mul_f32_e32 v38, v32, v33
	v_cvt_pk_bf16_f32 v34, v44, v40
	v_mul_f32_e32 v32, v39, v35
	v_mul_f32_e32 v33, v49, v37
	v_fmamk_f32 v36, v124, 0x3a800000, v152
	v_mul_f32_e32 v35, v32, v33
	v_cvt_pk_bf16_f32 v35, v38, v35
	v_rsq_f32_e32 v38, v36
	v_mad_i64_i32 v[36:37], s[30:31], v52, s60, v[120:121]
	v_cvt_pk_bf16_f32 v32, v53, v45
	v_mul_f32_e32 v39, 0xbfb8aa3b, v38
	v_mul_f32_e32 v40, v28, v39
	v_exp_f32_e32 v40, v40
	v_lshl_add_u64 v[36:37], v[36:37], 0, v[122:123]
	v_cvt_pk_bf16_f32 v33, v42, v43
	global_store_dwordx4 v[36:37], v[32:35], off nt
	v_add_u32_e32 v36, 0xa0, v144
	s_nop 0
	v_add_f32_e32 v32, 1.0, v40
	v_rcp_f32_e32 v35, v32
	v_mov_b32_e32 v32, v28
	v_mul_f32_e32 v28, v29, v39
	v_exp_f32_e32 v28, v28
	v_mul_f32_e32 v33, v38, v38
	v_mul_f32_e32 v34, v32, v24
	v_mul_f32_e32 v35, v33, v35
	v_add_f32_e32 v24, 1.0, v28
	v_mul_f32_e32 v37, v34, v35
	v_rcp_f32_e32 v35, v24
	v_mul_f32_e32 v24, v30, v39
	v_exp_f32_e32 v28, v24
	v_mov_b32_e32 v34, v25
	v_mul_f32_e32 v24, v29, v25
; DI u32x4 pack8(const f32x4 v0, const f32x4 v1) { u32x4 w; w.x = cvt_pk_bf16(v0[0], v0[1]); w.y = cvt_pk_bf16(v0[2], v0[3]); w.z = cvt_pk_bf16(v1[0], v1[1]); w.w = cvt_pk_bf16(v1[2], v1[3]); return w; }
;     DI void operator()(const f32x4 (&acc)[2][2][4][2], const Unit& u, int wr, int wc, int fr, int fq) const {
;     ...
; #pragma unroll
;         for (int ai = 0; ai < 2; ++ai)
; #pragma unroll
;             for (int m = 0; m < 4; ++m) {
;                 const size_t row = (size_t)(row0 + ai * 128 + m * 16);
;                 const float rs = __builtin_amdgcn_rsqf(ssv[ai * 4 + m] * (1.0f / 1024.0f) + EPS);
;                 const float c1 = -rs * 1.4426950408889634f, rs2 = rs * rs;
;                 f32x4 o[2];
; #pragma unroll
;                 for (int n = 0; n < 2; ++n)
; #pragma unroll
;                     for (int j = 0; j < 4; ++j) { const float ga = acc[ai][0][m][n][j], ua = acc[ai][1][m][n][j];
;                         o[n][j] = (ga * ua) * (rs2 * __builtin_amdgcn_rcpf(1.0f + __builtin_amdgcn_exp2f(ga * c1))); }
;                 __builtin_nontemporal_store(pack8(o[0], o[1]), (u32x4*)(GU + row * DFF + col0));
;             }
	v_mul_f32_e32 v25, v33, v35
	v_mul_f32_e32 v29, v24, v25
	v_add_f32_e32 v24, 1.0, v28
	v_rcp_f32_e32 v25, v24
	v_mul_f32_e32 v24, v31, v39
	v_exp_f32_e32 v28, v24
	v_mul_f32_e32 v24, v30, v26
	v_mul_f32_e32 v25, v33, v25
	v_mul_f32_e32 v26, v24, v25
	v_add_f32_e32 v24, 1.0, v28
	v_rcp_f32_e32 v25, v24
	v_mul_f32_e32 v24, v20, v39
	v_exp_f32_e32 v28, v24
	v_mul_f32_e32 v24, v31, v27
	v_mul_f32_e32 v25, v33, v25
	v_mov_b32_e32 v32, v20
	v_mul_f32_e32 v27, v24, v25
	v_add_f32_e32 v24, 1.0, v28
	v_mul_f32_e32 v20, v21, v39
	v_rcp_f32_e32 v25, v24
	v_exp_f32_e32 v20, v20
	v_mul_f32_e32 v24, v32, v16
	v_mul_f32_e32 v25, v33, v25
	v_add_f32_e32 v16, 1.0, v20
	v_mul_f32_e32 v28, v24, v25
	v_rcp_f32_e32 v25, v16
	v_mul_f32_e32 v16, v22, v39
	v_exp_f32_e32 v20, v16
	v_mul_f32_e32 v16, v21, v17
	v_mul_f32_e32 v17, v33, v25
	v_mul_f32_e32 v24, v16, v17
	v_add_f32_e32 v16, 1.0, v20
	v_rcp_f32_e32 v17, v16
	v_mul_f32_e32 v16, v23, v39
	v_exp_f32_e32 v20, v16
	v_mul_f32_e32 v16, v22, v18
	v_mul_f32_e32 v17, v33, v17
	v_mov_b32_e32 v32, v23
	v_add_f32_e32 v18, 1.0, v20
	v_rcp_f32_e32 v21, v18
	v_mul_f32_e32 v22, v16, v17
	v_cvt_pk_bf16_f32 v18, v28, v24
	v_mul_f32_e32 v16, v23, v19
	v_mul_f32_e32 v17, v33, v21
	v_fmamk_f32 v20, v104, 0x3a800000, v152
	v_mul_f32_e32 v19, v16, v17
	v_cvt_pk_bf16_f32 v19, v22, v19
	v_rsq_f32_e32 v22, v20
	v_mad_i64_i32 v[20:21], s[30:31], v36, s60, v[120:121]
	v_cvt_pk_bf16_f32 v16, v37, v29
	v_mul_f32_e32 v23, 0xbfb8aa3b, v22
	v_mul_f32_e32 v24, v12, v23
	v_exp_f32_e32 v24, v24
	v_lshl_add_u64 v[20:21], v[20:21], 0, v[122:123]
	v_cvt_pk_bf16_f32 v17, v26, v27
	global_store_dwordx4 v[20:21], v[16:19], off nt
	v_add_u32_e32 v20, 0xb0, v144
	s_nop 0
	v_add_f32_e32 v16, 1.0, v24
	v_rcp_f32_e32 v19, v16
	v_mov_b32_e32 v16, v12
	v_mul_f32_e32 v12, v13, v23
	v_exp_f32_e32 v12, v12
	v_mul_f32_e32 v17, v22, v22
	v_mul_f32_e32 v18, v16, v8
	v_mul_f32_e32 v19, v17, v19
	v_add_f32_e32 v8, 1.0, v12
	v_mul_f32_e32 v21, v18, v19
	v_rcp_f32_e32 v19, v8
	v_mul_f32_e32 v8, v14, v23
	v_exp_f32_e32 v12, v8
	v_mov_b32_e32 v18, v9
	v_mul_f32_e32 v8, v13, v9
	v_mul_f32_e32 v9, v17, v19
	v_mul_f32_e32 v13, v8, v9
	v_add_f32_e32 v8, 1.0, v12
	v_rcp_f32_e32 v9, v8
	v_mul_f32_e32 v8, v15, v23
	v_exp_f32_e32 v12, v8
	v_mul_f32_e32 v8, v14, v10
	v_mul_f32_e32 v9, v17, v9
	v_mul_f32_e32 v10, v8, v9
	v_add_f32_e32 v8, 1.0, v12
	v_rcp_f32_e32 v9, v8
	v_mul_f32_e32 v8, v4, v23
	v_exp_f32_e32 v12, v8
	v_mul_f32_e32 v8, v15, v11
	v_mul_f32_e32 v9, v17, v9
	v_mov_b32_e32 v16, v4
	v_mul_f32_e32 v11, v8, v9
	v_add_f32_e32 v8, 1.0, v12
	v_mul_f32_e32 v4, v5, v23
	v_rcp_f32_e32 v9, v8
	v_exp_f32_e32 v4, v4
	v_mul_f32_e32 v8, v16, v0
	v_mul_f32_e32 v9, v17, v9
	v_add_f32_e32 v0, 1.0, v4
	v_mul_f32_e32 v12, v8, v9
	v_rcp_f32_e32 v9, v0
	v_mul_f32_e32 v0, v6, v23
	v_exp_f32_e32 v4, v0
	v_mul_f32_e32 v0, v5, v1
	v_mul_f32_e32 v1, v17, v9
	v_mul_f32_e32 v8, v0, v1
	v_add_f32_e32 v0, 1.0, v4
	v_rcp_f32_e32 v1, v0
	v_mul_f32_e32 v0, v7, v23
	v_exp_f32_e32 v4, v0
	v_mul_f32_e32 v0, v6, v2
	v_mul_f32_e32 v1, v17, v1
	v_mov_b32_e32 v16, v7
	v_add_f32_e32 v2, 1.0, v4
	v_rcp_f32_e32 v5, v2
	v_mul_f32_e32 v6, v0, v1
	v_cvt_pk_bf16_f32 v2, v12, v8
	v_mul_f32_e32 v0, v7, v3
	v_mul_f32_e32 v1, v17, v5
	v_mad_i64_i32 v[4:5], s[30:31], v20, s60, v[120:121]
	v_mul_f32_e32 v3, v0, v1
	v_lshl_add_u64 v[4:5], v[4:5], 0, v[122:123]
	v_cvt_pk_bf16_f32 v0, v21, v13
	v_cvt_pk_bf16_f32 v1, v10, v11
	v_cvt_pk_bf16_f32 v3, v6, v3
	global_store_dwordx4 v[4:5], v[0:3], off nt
	s_cbranch_vccnz .LBB0_1381
	s_andn2_b64 vcc, exec, s[6:7]
	s_cbranch_vccnz .LBB0_1380
	s_barrier
	s_branch .LBB0_1380
